# K loops issue the next stage's LDS-DMA two groups per MFMA (front-loaded) on top of the weight-panel tile orders
# baseline (speedup 1.0000x reference)
; template <int NI, bool DEEP = true>
; DEV void gemm_tile(f32x16 (&acc)[2][NI], const bf16* __restrict__ A, int lda, const bf16* __restrict__ Bt, int ldb,
;                    int K, bf16* sA, bf16* sB) {
;     ...
;   G_LOAD(ra0, rb0, 0)
;   if (DEEP) {
;     if (64 < K) G_LOAD(ra1, rb1, 64)
;     for (int k0 = 0; k0 < K; k0 += 128) {
;       G_STEP(ra0, rb0, k0 + 128)
;       if (k0 + 64 < K) G_STEP(ra1, rb1, k0 + 192)
;     }
.Lg1k_loop:
	s_waitcnt vmcnt(0)
	s_barrier
	ds_read_b128 v[88:91], v74 offset:0
	ds_read_b128 v[80:83], v70 offset:0
	ds_read_b128 v[84:87], v70 offset:4096
	ds_read_b128 v[92:95], v74 offset:4096
	s_waitcnt lgkmcnt(2)
	v_mfma_f32_32x32x16_bf16 v[52:67], v[88:91], v[80:83], v[52:67]
	s_add_u32 m0, s16, 0x8000
	s_nop 0
	global_load_lds_dwordx4 v68, s[98:99]
	s_add_u32 m0, s16, 0x8400
	s_add_u32 s14, s98, 0x4000
	s_addc_u32 s15, s99, 0
	global_load_lds_dwordx4 v69, s[14:15]
	ds_read_b128 v[104:107], v75 offset:0
	ds_read_b128 v[96:99], v71 offset:0
	s_waitcnt lgkmcnt(3)
	v_mfma_f32_32x32x16_bf16 v[20:35], v[88:91], v[84:87], v[20:35]
	s_add_u32 m0, s16, 0x8800
	s_add_u32 s14, s98, 0x8000
	s_addc_u32 s15, s99, 0
	global_load_lds_dwordx4 v68, s[14:15]
	s_add_u32 m0, s16, 0x8c00
	s_add_u32 s14, s98, 0xc000
	s_addc_u32 s15, s99, 0
	global_load_lds_dwordx4 v69, s[14:15]
	ds_read_b128 v[100:103], v71 offset:4096
	s_waitcnt lgkmcnt(3)
	v_mfma_f32_32x32x16_bf16 v[36:51], v[92:95], v[80:83], v[36:51]
	s_add_u32 m0, s16, 0xd840
	s_nop 0
	global_load_lds_dwordx4 v68, s[100:101]
	s_add_u32 m0, s16, 0xdc40
	s_add_u32 s14, s100, 0x4000
	s_addc_u32 s15, s101, 0
	global_load_lds_dwordx4 v69, s[14:15]
	ds_read_b128 v[108:111], v75 offset:4096
	v_mfma_f32_32x32x16_bf16 v[4:19], v[92:95], v[84:87], v[4:19]
	s_add_u32 m0, s16, 0xe040
	s_add_u32 s14, s100, 0x8000
	s_addc_u32 s15, s101, 0
	global_load_lds_dwordx4 v68, s[14:15]
	s_add_u32 m0, s16, 0xe440
	s_add_u32 s14, s100, 0xc000
	s_addc_u32 s15, s101, 0
	global_load_lds_dwordx4 v69, s[14:15]
	s_waitcnt lgkmcnt(2)
	v_mfma_f32_32x32x16_bf16 v[52:67], v[104:107], v[96:99], v[52:67]
	s_add_u32 s98, s98, 0x80
	s_addc_u32 s99, s99, 0
	s_add_u32 s100, s100, 0x80
	s_addc_u32 s101, s101, 0
	ds_read_b128 v[120:123], v76 offset:0
	ds_read_b128 v[112:115], v72 offset:0
	s_waitcnt lgkmcnt(3)
	v_mfma_f32_32x32x16_bf16 v[20:35], v[104:107], v[100:103], v[20:35]
	ds_read_b128 v[116:119], v72 offset:4096
	s_waitcnt lgkmcnt(3)
	v_mfma_f32_32x32x16_bf16 v[36:51], v[108:111], v[96:99], v[36:51]
	ds_read_b128 v[124:127], v76 offset:4096
	v_mfma_f32_32x32x16_bf16 v[4:19], v[108:111], v[100:103], v[4:19]
	s_waitcnt lgkmcnt(2)
	v_mfma_f32_32x32x16_bf16 v[52:67], v[120:123], v[112:115], v[52:67]
	ds_read_b128 v[88:91], v77 offset:0
	ds_read_b128 v[80:83], v73 offset:0
	s_waitcnt lgkmcnt(3)
	v_mfma_f32_32x32x16_bf16 v[20:35], v[120:123], v[116:119], v[20:35]
	ds_read_b128 v[84:87], v73 offset:4096
	s_waitcnt lgkmcnt(3)
	v_mfma_f32_32x32x16_bf16 v[36:51], v[124:127], v[112:115], v[36:51]
	ds_read_b128 v[92:95], v77 offset:4096
	v_mfma_f32_32x32x16_bf16 v[4:19], v[124:127], v[116:119], v[4:19]
	s_waitcnt lgkmcnt(2)
	v_mfma_f32_32x32x16_bf16 v[52:67], v[88:91], v[80:83], v[52:67]
	s_waitcnt lgkmcnt(1)
	v_mfma_f32_32x32x16_bf16 v[20:35], v[88:91], v[84:87], v[20:35]
	s_waitcnt lgkmcnt(0)
	v_mfma_f32_32x32x16_bf16 v[36:51], v[92:95], v[80:83], v[36:51]
	v_mfma_f32_32x32x16_bf16 v[4:19], v[92:95], v[84:87], v[4:19]
	s_waitcnt vmcnt(0)
	s_barrier
	s_cmp_eq_u32 s11, 7
	s_cbranch_scc1 .Lg1k_nodma
	ds_read_b128 v[88:91], v74 offset:38976
	ds_read_b128 v[80:83], v70 offset:32768
	ds_read_b128 v[84:87], v70 offset:36864
	ds_read_b128 v[92:95], v74 offset:43072
	s_waitcnt lgkmcnt(2)
	v_mfma_f32_32x32x16_bf16 v[52:67], v[88:91], v[80:83], v[52:67]
	s_add_u32 m0, s16, 0x0
	s_nop 0
	global_load_lds_dwordx4 v68, s[98:99]
	s_add_u32 m0, s16, 0x400
	s_add_u32 s14, s98, 0x4000
	s_addc_u32 s15, s99, 0
	global_load_lds_dwordx4 v69, s[14:15]
	ds_read_b128 v[104:107], v75 offset:38976
	ds_read_b128 v[96:99], v71 offset:32768
	s_waitcnt lgkmcnt(3)
	v_mfma_f32_32x32x16_bf16 v[20:35], v[88:91], v[84:87], v[20:35]
	s_add_u32 m0, s16, 0x800
	s_add_u32 s14, s98, 0x8000
	s_addc_u32 s15, s99, 0
	global_load_lds_dwordx4 v68, s[14:15]
	s_add_u32 m0, s16, 0xc00
	s_add_u32 s14, s98, 0xc000
	s_addc_u32 s15, s99, 0
	global_load_lds_dwordx4 v69, s[14:15]
	ds_read_b128 v[100:103], v71 offset:36864
	s_waitcnt lgkmcnt(3)
	v_mfma_f32_32x32x16_bf16 v[36:51], v[92:95], v[80:83], v[36:51]
	s_add_u32 m0, s16, 0x4000
	s_nop 0
	global_load_lds_dwordx4 v68, s[100:101]
	s_add_u32 m0, s16, 0x4400
	s_add_u32 s14, s100, 0x4000
	s_addc_u32 s15, s101, 0
	global_load_lds_dwordx4 v69, s[14:15]
	ds_read_b128 v[108:111], v75 offset:43072
	v_mfma_f32_32x32x16_bf16 v[4:19], v[92:95], v[84:87], v[4:19]
	s_add_u32 m0, s16, 0x4800
	s_add_u32 s14, s100, 0x8000
	s_addc_u32 s15, s101, 0
	global_load_lds_dwordx4 v68, s[14:15]
	s_add_u32 m0, s16, 0x4c00
	s_add_u32 s14, s100, 0xc000
	s_addc_u32 s15, s101, 0
	global_load_lds_dwordx4 v69, s[14:15]
	s_waitcnt lgkmcnt(2)
	v_mfma_f32_32x32x16_bf16 v[52:67], v[104:107], v[96:99], v[52:67]
	s_add_u32 s98, s98, 0x80
	s_addc_u32 s99, s99, 0
	s_add_u32 s100, s100, 0x80
	s_addc_u32 s101, s101, 0
	ds_read_b128 v[120:123], v76 offset:38976
	ds_read_b128 v[112:115], v72 offset:32768
	s_waitcnt lgkmcnt(3)
	v_mfma_f32_32x32x16_bf16 v[20:35], v[104:107], v[100:103], v[20:35]
	ds_read_b128 v[116:119], v72 offset:36864
	s_waitcnt lgkmcnt(3)
	v_mfma_f32_32x32x16_bf16 v[36:51], v[108:111], v[96:99], v[36:51]
	ds_read_b128 v[124:127], v76 offset:43072
	v_mfma_f32_32x32x16_bf16 v[4:19], v[108:111], v[100:103], v[4:19]
	s_waitcnt lgkmcnt(2)
	v_mfma_f32_32x32x16_bf16 v[52:67], v[120:123], v[112:115], v[52:67]
	ds_read_b128 v[88:91], v77 offset:38976
	ds_read_b128 v[80:83], v73 offset:32768
	s_waitcnt lgkmcnt(3)
	v_mfma_f32_32x32x16_bf16 v[20:35], v[120:123], v[116:119], v[20:35]
	ds_read_b128 v[84:87], v73 offset:36864
	s_waitcnt lgkmcnt(3)
	v_mfma_f32_32x32x16_bf16 v[36:51], v[124:127], v[112:115], v[36:51]
	ds_read_b128 v[92:95], v77 offset:43072
	v_mfma_f32_32x32x16_bf16 v[4:19], v[124:127], v[116:119], v[4:19]
	s_waitcnt lgkmcnt(2)
	v_mfma_f32_32x32x16_bf16 v[52:67], v[88:91], v[80:83], v[52:67]
	s_waitcnt lgkmcnt(1)
	v_mfma_f32_32x32x16_bf16 v[20:35], v[88:91], v[84:87], v[20:35]
	s_waitcnt lgkmcnt(0)
	v_mfma_f32_32x32x16_bf16 v[36:51], v[92:95], v[80:83], v[36:51]
	v_mfma_f32_32x32x16_bf16 v[4:19], v[92:95], v[84:87], v[4:19]
	s_branch .Lg1k_next

; template <int NI, bool DEEP = true>
; DEV void gemm_tile(f32x16 (&acc)[2][NI], const bf16* __restrict__ A, int lda, const bf16* __restrict__ Bt, int ldb,
;                    int K, bf16* sA, bf16* sB) {
;     ...
;   G_LOAD(ra0, rb0, 0)
;   if (DEEP) {
;     if (64 < K) G_LOAD(ra1, rb1, 64)
;     for (int k0 = 0; k0 < K; k0 += 128) {
;       G_STEP(ra0, rb0, k0 + 128)
;       if (k0 + 64 < K) G_STEP(ra1, rb1, k0 + 192)
;     }
.Lgtk_loop:
	s_waitcnt vmcnt(0)
	s_barrier
	ds_read_b128 v[88:91], v74 offset:0
	ds_read_b128 v[80:83], v70 offset:0
	ds_read_b128 v[84:87], v70 offset:4096
	ds_read_b128 v[92:95], v74 offset:4096
	s_waitcnt lgkmcnt(2)
	v_mfma_f32_32x32x16_bf16 v[52:67], v[88:91], v[80:83], v[52:67]
	s_add_u32 m0, s0, 0x8000
	s_nop 0
	global_load_lds_dwordx4 v68, s[98:99]
	s_add_u32 m0, s0, 0x8400
	s_add_u32 s14, s98, 0x4000
	s_addc_u32 s15, s99, 0
	global_load_lds_dwordx4 v69, s[14:15]
	ds_read_b128 v[104:107], v75 offset:0
	ds_read_b128 v[96:99], v71 offset:0
	s_waitcnt lgkmcnt(3)
	v_mfma_f32_32x32x16_bf16 v[20:35], v[88:91], v[84:87], v[20:35]
	s_add_u32 m0, s0, 0x8800
	s_add_u32 s14, s98, 0x8000
	s_addc_u32 s15, s99, 0
	global_load_lds_dwordx4 v68, s[14:15]
	s_add_u32 m0, s0, 0x8c00
	s_add_u32 s14, s98, 0xc000
	s_addc_u32 s15, s99, 0
	global_load_lds_dwordx4 v69, s[14:15]
	ds_read_b128 v[100:103], v71 offset:4096
	s_waitcnt lgkmcnt(3)
	v_mfma_f32_32x32x16_bf16 v[36:51], v[92:95], v[80:83], v[36:51]
	s_add_u32 m0, s0, 0xd840
	s_nop 0
	global_load_lds_dwordx4 v68, s[100:101]
	s_add_u32 m0, s0, 0xdc40
	s_add_u32 s14, s100, 0x4000
	s_addc_u32 s15, s101, 0
	global_load_lds_dwordx4 v69, s[14:15]
	ds_read_b128 v[108:111], v75 offset:4096
	v_mfma_f32_32x32x16_bf16 v[4:19], v[92:95], v[84:87], v[4:19]
	s_add_u32 m0, s0, 0xe040
	s_add_u32 s14, s100, 0x8000
	s_addc_u32 s15, s101, 0
	global_load_lds_dwordx4 v68, s[14:15]
	s_add_u32 m0, s0, 0xe440
	s_add_u32 s14, s100, 0xc000
	s_addc_u32 s15, s101, 0
	global_load_lds_dwordx4 v69, s[14:15]
	s_waitcnt lgkmcnt(2)
	v_mfma_f32_32x32x16_bf16 v[52:67], v[104:107], v[96:99], v[52:67]
	s_add_u32 s98, s98, 0x80
	s_addc_u32 s99, s99, 0
	s_add_u32 s100, s100, 0x80
	s_addc_u32 s101, s101, 0
	ds_read_b128 v[120:123], v76 offset:0
	ds_read_b128 v[112:115], v72 offset:0
	s_waitcnt lgkmcnt(3)
	v_mfma_f32_32x32x16_bf16 v[20:35], v[104:107], v[100:103], v[20:35]
	ds_read_b128 v[116:119], v72 offset:4096
	s_waitcnt lgkmcnt(3)
	v_mfma_f32_32x32x16_bf16 v[36:51], v[108:111], v[96:99], v[36:51]
	ds_read_b128 v[124:127], v76 offset:4096
	v_mfma_f32_32x32x16_bf16 v[4:19], v[108:111], v[100:103], v[4:19]
	s_waitcnt lgkmcnt(2)
	v_mfma_f32_32x32x16_bf16 v[52:67], v[120:123], v[112:115], v[52:67]
	ds_read_b128 v[88:91], v77 offset:0
	ds_read_b128 v[80:83], v73 offset:0
	s_waitcnt lgkmcnt(3)
	v_mfma_f32_32x32x16_bf16 v[20:35], v[120:123], v[116:119], v[20:35]
	ds_read_b128 v[84:87], v73 offset:4096
	s_waitcnt lgkmcnt(3)
	v_mfma_f32_32x32x16_bf16 v[36:51], v[124:127], v[112:115], v[36:51]
	ds_read_b128 v[92:95], v77 offset:4096
	v_mfma_f32_32x32x16_bf16 v[4:19], v[124:127], v[116:119], v[4:19]
	s_waitcnt lgkmcnt(2)
	v_mfma_f32_32x32x16_bf16 v[52:67], v[88:91], v[80:83], v[52:67]
	s_waitcnt lgkmcnt(1)
	v_mfma_f32_32x32x16_bf16 v[20:35], v[88:91], v[84:87], v[20:35]
	s_waitcnt lgkmcnt(0)
	v_mfma_f32_32x32x16_bf16 v[36:51], v[92:95], v[80:83], v[36:51]
	v_mfma_f32_32x32x16_bf16 v[4:19], v[92:95], v[84:87], v[4:19]
	s_waitcnt vmcnt(0)
	s_barrier
	s_cmp_eq_u32 s11, 7
	s_cbranch_scc1 .Lgtk_nodma
	ds_read_b128 v[88:91], v74 offset:38976
	ds_read_b128 v[80:83], v70 offset:32768
	ds_read_b128 v[84:87], v70 offset:36864
	ds_read_b128 v[92:95], v74 offset:43072
	s_waitcnt lgkmcnt(2)
	v_mfma_f32_32x32x16_bf16 v[52:67], v[88:91], v[80:83], v[52:67]
	s_add_u32 m0, s0, 0x0
	s_nop 0
	global_load_lds_dwordx4 v68, s[98:99]
	s_add_u32 m0, s0, 0x400
	s_add_u32 s14, s98, 0x4000
	s_addc_u32 s15, s99, 0
	global_load_lds_dwordx4 v69, s[14:15]
	ds_read_b128 v[104:107], v75 offset:38976
	ds_read_b128 v[96:99], v71 offset:32768
	s_waitcnt lgkmcnt(3)
	v_mfma_f32_32x32x16_bf16 v[20:35], v[88:91], v[84:87], v[20:35]
	s_add_u32 m0, s0, 0x800
	s_add_u32 s14, s98, 0x8000
	s_addc_u32 s15, s99, 0
	global_load_lds_dwordx4 v68, s[14:15]
	s_add_u32 m0, s0, 0xc00
	s_add_u32 s14, s98, 0xc000
	s_addc_u32 s15, s99, 0
	global_load_lds_dwordx4 v69, s[14:15]
	ds_read_b128 v[100:103], v71 offset:36864
	s_waitcnt lgkmcnt(3)
	v_mfma_f32_32x32x16_bf16 v[36:51], v[92:95], v[80:83], v[36:51]
	s_add_u32 m0, s0, 0x4000
	s_nop 0
	global_load_lds_dwordx4 v68, s[100:101]
	s_add_u32 m0, s0, 0x4400
	s_add_u32 s14, s100, 0x4000
	s_addc_u32 s15, s101, 0
	global_load_lds_dwordx4 v69, s[14:15]
	ds_read_b128 v[108:111], v75 offset:43072
	v_mfma_f32_32x32x16_bf16 v[4:19], v[92:95], v[84:87], v[4:19]
	s_add_u32 m0, s0, 0x4800
	s_add_u32 s14, s100, 0x8000
	s_addc_u32 s15, s101, 0
	global_load_lds_dwordx4 v68, s[14:15]
	s_add_u32 m0, s0, 0x4c00
	s_add_u32 s14, s100, 0xc000
	s_addc_u32 s15, s101, 0
	global_load_lds_dwordx4 v69, s[14:15]
	s_waitcnt lgkmcnt(2)
	v_mfma_f32_32x32x16_bf16 v[52:67], v[104:107], v[96:99], v[52:67]
	s_add_u32 s98, s98, 0x80
	s_addc_u32 s99, s99, 0
	s_add_u32 s100, s100, 0x80
	s_addc_u32 s101, s101, 0
	ds_read_b128 v[120:123], v76 offset:38976
	ds_read_b128 v[112:115], v72 offset:32768
	s_waitcnt lgkmcnt(3)
	v_mfma_f32_32x32x16_bf16 v[20:35], v[104:107], v[100:103], v[20:35]
	ds_read_b128 v[116:119], v72 offset:36864
	s_waitcnt lgkmcnt(3)
	v_mfma_f32_32x32x16_bf16 v[36:51], v[108:111], v[96:99], v[36:51]
	ds_read_b128 v[124:127], v76 offset:43072
	v_mfma_f32_32x32x16_bf16 v[4:19], v[108:111], v[100:103], v[4:19]
	s_waitcnt lgkmcnt(2)
	v_mfma_f32_32x32x16_bf16 v[52:67], v[120:123], v[112:115], v[52:67]
	ds_read_b128 v[88:91], v77 offset:38976
	ds_read_b128 v[80:83], v73 offset:32768
	s_waitcnt lgkmcnt(3)
	v_mfma_f32_32x32x16_bf16 v[20:35], v[120:123], v[116:119], v[20:35]
	ds_read_b128 v[84:87], v73 offset:36864
	s_waitcnt lgkmcnt(3)
	v_mfma_f32_32x32x16_bf16 v[36:51], v[124:127], v[112:115], v[36:51]
	ds_read_b128 v[92:95], v77 offset:43072
	v_mfma_f32_32x32x16_bf16 v[4:19], v[124:127], v[116:119], v[4:19]
	s_waitcnt lgkmcnt(2)
	v_mfma_f32_32x32x16_bf16 v[52:67], v[88:91], v[80:83], v[52:67]
	s_waitcnt lgkmcnt(1)
	v_mfma_f32_32x32x16_bf16 v[20:35], v[88:91], v[84:87], v[20:35]
	s_waitcnt lgkmcnt(0)
	v_mfma_f32_32x32x16_bf16 v[36:51], v[92:95], v[80:83], v[36:51]
	v_mfma_f32_32x32x16_bf16 v[4:19], v[92:95], v[84:87], v[4:19]
	s_branch .Lgtk_next

; template <int NI, bool DEEP = true>
; DEV void gemm_tile(f32x16 (&acc)[2][NI], const bf16* __restrict__ A, int lda, const bf16* __restrict__ Bt, int ldb,
;                    int K, bf16* sA, bf16* sB) {
;     ...
;   G_LOAD(ra0, rb0, 0)
;   if (DEEP) {
;     if (64 < K) G_LOAD(ra1, rb1, 64)
;     for (int k0 = 0; k0 < K; k0 += 128) {
;       G_STEP(ra0, rb0, k0 + 128)
;       if (k0 + 64 < K) G_STEP(ra1, rb1, k0 + 192)
;     }
.Lmak_loop:
	s_waitcnt vmcnt(0)
	s_barrier
	ds_read_b128 v[40:43], v26 offset:0
	ds_read_b128 v[32:35], v22 offset:0
	ds_read_b128 v[36:39], v22 offset:4096
	ds_read_b128 v[44:47], v26 offset:4096
	s_waitcnt lgkmcnt(2)
	v_mfma_f32_32x32x16_bf16 v[116:131], v[40:43], v[32:35], v[116:131]
	s_add_u32 m0, s0, 0x8000
	s_nop 0
	global_load_lds_dwordx4 v20, s[98:99]
	s_add_u32 m0, s0, 0x8400
	s_add_u32 s34, s98, 0x4000
	s_addc_u32 s35, s99, 0
	global_load_lds_dwordx4 v21, s[34:35]
	ds_read_b128 v[56:59], v27 offset:0
	ds_read_b128 v[48:51], v23 offset:0
	s_waitcnt lgkmcnt(3)
	v_mfma_f32_32x32x16_bf16 v[68:83], v[40:43], v[36:39], v[68:83]
	s_add_u32 m0, s0, 0x8800
	s_add_u32 s34, s98, 0x8000
	s_addc_u32 s35, s99, 0
	global_load_lds_dwordx4 v20, s[34:35]
	s_add_u32 m0, s0, 0x8c00
	s_add_u32 s34, s98, 0xc000
	s_addc_u32 s35, s99, 0
	global_load_lds_dwordx4 v21, s[34:35]
	ds_read_b128 v[52:55], v23 offset:4096
	s_waitcnt lgkmcnt(3)
	v_mfma_f32_32x32x16_bf16 v[100:115], v[44:47], v[32:35], v[100:115]
	s_add_u32 m0, s0, 0xd840
	s_nop 0
	global_load_lds_dwordx4 v20, s[100:101]
	s_add_u32 m0, s0, 0xdc40
	s_add_u32 s34, s100, 0x4000
	s_addc_u32 s35, s101, 0
	global_load_lds_dwordx4 v21, s[34:35]
	ds_read_b128 v[60:63], v27 offset:4096
	v_mfma_f32_32x32x16_bf16 v[4:19], v[44:47], v[36:39], v[4:19]
	s_add_u32 m0, s0, 0xe040
	s_add_u32 s34, s100, 0x8000
	s_addc_u32 s35, s101, 0
	global_load_lds_dwordx4 v20, s[34:35]
	s_add_u32 m0, s0, 0xe440
	s_add_u32 s34, s100, 0xc000
	s_addc_u32 s35, s101, 0
	global_load_lds_dwordx4 v21, s[34:35]
	s_waitcnt lgkmcnt(2)
	v_mfma_f32_32x32x16_bf16 v[116:131], v[56:59], v[48:51], v[116:131]
	s_add_u32 s98, s98, 0x80
	s_addc_u32 s99, s99, 0
	s_add_u32 s100, s100, 0x80
	s_addc_u32 s101, s101, 0
	ds_read_b128 v[92:95], v28 offset:0
	ds_read_b128 v[84:87], v24 offset:0
	s_waitcnt lgkmcnt(3)
	v_mfma_f32_32x32x16_bf16 v[68:83], v[56:59], v[52:55], v[68:83]
	ds_read_b128 v[88:91], v24 offset:4096
	s_waitcnt lgkmcnt(3)
	v_mfma_f32_32x32x16_bf16 v[100:115], v[60:63], v[48:51], v[100:115]
	ds_read_b128 v[96:99], v28 offset:4096
	v_mfma_f32_32x32x16_bf16 v[4:19], v[60:63], v[52:55], v[4:19]
	s_waitcnt lgkmcnt(2)
	v_mfma_f32_32x32x16_bf16 v[116:131], v[92:95], v[84:87], v[116:131]
	ds_read_b128 v[40:43], v29 offset:0
	ds_read_b128 v[32:35], v25 offset:0
	s_waitcnt lgkmcnt(3)
	v_mfma_f32_32x32x16_bf16 v[68:83], v[92:95], v[88:91], v[68:83]
	ds_read_b128 v[36:39], v25 offset:4096
	s_waitcnt lgkmcnt(3)
	v_mfma_f32_32x32x16_bf16 v[100:115], v[96:99], v[84:87], v[100:115]
	ds_read_b128 v[44:47], v29 offset:4096
	v_mfma_f32_32x32x16_bf16 v[4:19], v[96:99], v[88:91], v[4:19]
	s_waitcnt lgkmcnt(2)
	v_mfma_f32_32x32x16_bf16 v[116:131], v[40:43], v[32:35], v[116:131]
	s_waitcnt lgkmcnt(1)
	v_mfma_f32_32x32x16_bf16 v[68:83], v[40:43], v[36:39], v[68:83]
	s_waitcnt lgkmcnt(0)
	v_mfma_f32_32x32x16_bf16 v[100:115], v[44:47], v[32:35], v[100:115]
	v_mfma_f32_32x32x16_bf16 v[4:19], v[44:47], v[36:39], v[4:19]
	s_waitcnt vmcnt(0)
	s_barrier
	s_cmp_eq_u32 s28, 7
	s_cbranch_scc1 .Lmak_nodma
	ds_read_b128 v[40:43], v26 offset:38976
	ds_read_b128 v[32:35], v22 offset:32768
	ds_read_b128 v[36:39], v22 offset:36864
	ds_read_b128 v[44:47], v26 offset:43072
	s_waitcnt lgkmcnt(2)
	v_mfma_f32_32x32x16_bf16 v[116:131], v[40:43], v[32:35], v[116:131]
	s_add_u32 m0, s0, 0x0
	s_nop 0
	global_load_lds_dwordx4 v20, s[98:99]
	s_add_u32 m0, s0, 0x400
	s_add_u32 s34, s98, 0x4000
	s_addc_u32 s35, s99, 0
	global_load_lds_dwordx4 v21, s[34:35]
	ds_read_b128 v[56:59], v27 offset:38976
	ds_read_b128 v[48:51], v23 offset:32768
	s_waitcnt lgkmcnt(3)
	v_mfma_f32_32x32x16_bf16 v[68:83], v[40:43], v[36:39], v[68:83]
	s_add_u32 m0, s0, 0x800
	s_add_u32 s34, s98, 0x8000
	s_addc_u32 s35, s99, 0
	global_load_lds_dwordx4 v20, s[34:35]
	s_add_u32 m0, s0, 0xc00
	s_add_u32 s34, s98, 0xc000
	s_addc_u32 s35, s99, 0
	global_load_lds_dwordx4 v21, s[34:35]
	ds_read_b128 v[52:55], v23 offset:36864
	s_waitcnt lgkmcnt(3)
	v_mfma_f32_32x32x16_bf16 v[100:115], v[44:47], v[32:35], v[100:115]
	s_add_u32 m0, s0, 0x4000
	s_nop 0
	global_load_lds_dwordx4 v20, s[100:101]
	s_add_u32 m0, s0, 0x4400
	s_add_u32 s34, s100, 0x4000
	s_addc_u32 s35, s101, 0
	global_load_lds_dwordx4 v21, s[34:35]
	ds_read_b128 v[60:63], v27 offset:43072
	v_mfma_f32_32x32x16_bf16 v[4:19], v[44:47], v[36:39], v[4:19]
	s_add_u32 m0, s0, 0x4800
	s_add_u32 s34, s100, 0x8000
	s_addc_u32 s35, s101, 0
	global_load_lds_dwordx4 v20, s[34:35]
	s_add_u32 m0, s0, 0x4c00
	s_add_u32 s34, s100, 0xc000
	s_addc_u32 s35, s101, 0
	global_load_lds_dwordx4 v21, s[34:35]
	s_waitcnt lgkmcnt(2)
	v_mfma_f32_32x32x16_bf16 v[116:131], v[56:59], v[48:51], v[116:131]
	s_add_u32 s98, s98, 0x80
	s_addc_u32 s99, s99, 0
	s_add_u32 s100, s100, 0x80
	s_addc_u32 s101, s101, 0
	ds_read_b128 v[92:95], v28 offset:38976
	ds_read_b128 v[84:87], v24 offset:32768
	s_waitcnt lgkmcnt(3)
	v_mfma_f32_32x32x16_bf16 v[68:83], v[56:59], v[52:55], v[68:83]
	ds_read_b128 v[88:91], v24 offset:36864
	s_waitcnt lgkmcnt(3)
	v_mfma_f32_32x32x16_bf16 v[100:115], v[60:63], v[48:51], v[100:115]
	ds_read_b128 v[96:99], v28 offset:43072
	v_mfma_f32_32x32x16_bf16 v[4:19], v[60:63], v[52:55], v[4:19]
	s_waitcnt lgkmcnt(2)
	v_mfma_f32_32x32x16_bf16 v[116:131], v[92:95], v[84:87], v[116:131]
	ds_read_b128 v[40:43], v29 offset:38976
	ds_read_b128 v[32:35], v25 offset:32768
	s_waitcnt lgkmcnt(3)
	v_mfma_f32_32x32x16_bf16 v[68:83], v[92:95], v[88:91], v[68:83]
	ds_read_b128 v[36:39], v25 offset:36864
	s_waitcnt lgkmcnt(3)
	v_mfma_f32_32x32x16_bf16 v[100:115], v[96:99], v[84:87], v[100:115]
	ds_read_b128 v[44:47], v29 offset:43072
	v_mfma_f32_32x32x16_bf16 v[4:19], v[96:99], v[88:91], v[4:19]
	s_waitcnt lgkmcnt(2)
	v_mfma_f32_32x32x16_bf16 v[116:131], v[40:43], v[32:35], v[116:131]
	s_waitcnt lgkmcnt(1)
	v_mfma_f32_32x32x16_bf16 v[68:83], v[40:43], v[36:39], v[68:83]
	s_waitcnt lgkmcnt(0)
	v_mfma_f32_32x32x16_bf16 v[100:115], v[44:47], v[32:35], v[100:115]
	v_mfma_f32_32x32x16_bf16 v[4:19], v[44:47], v[36:39], v[4:19]
	s_branch .Lmak_next

; template <int NI, bool DEEP = true>
; DEV void gemm_tile(f32x16 (&acc)[2][NI], const bf16* __restrict__ A, int lda, const bf16* __restrict__ Bt, int ldb,
;                    int K, bf16* sA, bf16* sB) {
;     ...
;   G_LOAD(ra0, rb0, 0)
;   if (DEEP) {
;     if (64 < K) G_LOAD(ra1, rb1, 64)
;     for (int k0 = 0; k0 < K; k0 += 128) {
;       G_STEP(ra0, rb0, k0 + 128)
;       if (k0 + 64 < K) G_STEP(ra1, rb1, k0 + 192)
;     }
;   } else {
;     for (int k0 = 0; k0 < K; k0 += 64) G_STEP(ra0, rb0, k0 + 64)
.Lmbk_loop:
	s_waitcnt vmcnt(0)
	s_barrier
	ds_read_b128 v[156:159], v142 offset:0
	ds_read_b128 v[148:151], v138 offset:0
	ds_read_b128 v[152:155], v138 offset:4096
	ds_read_b128 v[160:163], v142 offset:4096
	s_waitcnt lgkmcnt(2)
	v_mfma_f32_32x32x16_bf16 v[84:99], v[156:159], v[148:151], v[84:99]
	s_add_u32 m0, s28, 0x8000
	s_nop 0
	global_load_lds_dwordx4 v134, s[98:99]
	s_add_u32 m0, s28, 0x8400
	s_add_u32 s34, s98, s0
	s_addc_u32 s35, s99, 0
	global_load_lds_dwordx4 v135, s[34:35]
	ds_read_b128 v[172:175], v143 offset:0
	ds_read_b128 v[164:167], v139 offset:0
	s_waitcnt lgkmcnt(3)
	v_mfma_f32_32x32x16_bf16 v[36:51], v[156:159], v[152:155], v[36:51]
	s_add_u32 m0, s28, 0x8800
	s_add_u32 s34, s34, s0
	s_addc_u32 s35, s35, 0
	global_load_lds_dwordx4 v134, s[34:35]
	s_add_u32 m0, s28, 0x8c00
	s_add_u32 s34, s34, s0
	s_addc_u32 s35, s35, 0
	global_load_lds_dwordx4 v135, s[34:35]
	ds_read_b128 v[168:171], v139 offset:4096
	s_waitcnt lgkmcnt(3)
	v_mfma_f32_32x32x16_bf16 v[52:67], v[160:163], v[148:151], v[52:67]
	s_add_u32 m0, s28, 0xd840
	s_nop 0
	global_load_lds_dwordx4 v136, s[100:101]
	s_add_u32 m0, s28, 0xdc40
	s_add_u32 s34, s100, 0x2000
	s_addc_u32 s35, s101, 0
	global_load_lds_dwordx4 v137, s[34:35]
	ds_read_b128 v[176:179], v143 offset:4096
	v_mfma_f32_32x32x16_bf16 v[20:35], v[160:163], v[152:155], v[20:35]
	s_add_u32 m0, s28, 0xe040
	s_add_u32 s34, s100, 0x4000
	s_addc_u32 s35, s101, 0
	global_load_lds_dwordx4 v136, s[34:35]
	s_add_u32 m0, s28, 0xe440
	s_add_u32 s34, s100, 0x6000
	s_addc_u32 s35, s101, 0
	global_load_lds_dwordx4 v137, s[34:35]
	s_waitcnt lgkmcnt(2)
	v_mfma_f32_32x32x16_bf16 v[84:99], v[172:175], v[164:167], v[84:99]
	s_add_u32 s98, s98, 0x80
	s_addc_u32 s99, s99, 0
	s_add_u32 s100, s100, 0x80
	s_addc_u32 s101, s101, 0
	ds_read_b128 v[188:191], v144 offset:0
	ds_read_b128 v[180:183], v140 offset:0
	s_waitcnt lgkmcnt(3)
	v_mfma_f32_32x32x16_bf16 v[36:51], v[172:175], v[168:171], v[36:51]
	ds_read_b128 v[184:187], v140 offset:4096
	s_waitcnt lgkmcnt(3)
	v_mfma_f32_32x32x16_bf16 v[52:67], v[176:179], v[164:167], v[52:67]
	ds_read_b128 v[210:213], v144 offset:4096
	v_mfma_f32_32x32x16_bf16 v[20:35], v[176:179], v[168:171], v[20:35]
	s_waitcnt lgkmcnt(2)
	v_mfma_f32_32x32x16_bf16 v[84:99], v[188:191], v[180:183], v[84:99]
	ds_read_b128 v[156:159], v145 offset:0
	ds_read_b128 v[148:151], v141 offset:0
	s_waitcnt lgkmcnt(3)
	v_mfma_f32_32x32x16_bf16 v[36:51], v[188:191], v[184:187], v[36:51]
	ds_read_b128 v[152:155], v141 offset:4096
	s_waitcnt lgkmcnt(3)
	v_mfma_f32_32x32x16_bf16 v[52:67], v[210:213], v[180:183], v[52:67]
	ds_read_b128 v[160:163], v145 offset:4096
	v_mfma_f32_32x32x16_bf16 v[20:35], v[210:213], v[184:187], v[20:35]
	s_waitcnt lgkmcnt(2)
	v_mfma_f32_32x32x16_bf16 v[84:99], v[156:159], v[148:151], v[84:99]
	s_waitcnt lgkmcnt(1)
	v_mfma_f32_32x32x16_bf16 v[36:51], v[156:159], v[152:155], v[36:51]
	s_waitcnt lgkmcnt(0)
	v_mfma_f32_32x32x16_bf16 v[52:67], v[160:163], v[148:151], v[52:67]
	v_mfma_f32_32x32x16_bf16 v[20:35], v[160:163], v[152:155], v[20:35]
	s_waitcnt vmcnt(0)
	s_barrier
	s_cmp_eq_u32 s57, 3
	s_cbranch_scc1 .Lmbk_nodma
	ds_read_b128 v[156:159], v142 offset:38976
	ds_read_b128 v[148:151], v138 offset:32768
	ds_read_b128 v[152:155], v138 offset:36864
	ds_read_b128 v[160:163], v142 offset:43072
	s_waitcnt lgkmcnt(2)
	v_mfma_f32_32x32x16_bf16 v[84:99], v[156:159], v[148:151], v[84:99]
	s_add_u32 m0, s28, 0x0
	s_nop 0
	global_load_lds_dwordx4 v134, s[98:99]
	s_add_u32 m0, s28, 0x400
	s_add_u32 s34, s98, s0
	s_addc_u32 s35, s99, 0
	global_load_lds_dwordx4 v135, s[34:35]
	ds_read_b128 v[172:175], v143 offset:38976
	ds_read_b128 v[164:167], v139 offset:32768
	s_waitcnt lgkmcnt(3)
	v_mfma_f32_32x32x16_bf16 v[36:51], v[156:159], v[152:155], v[36:51]
	s_add_u32 m0, s28, 0x800
	s_add_u32 s34, s34, s0
	s_addc_u32 s35, s35, 0
	global_load_lds_dwordx4 v134, s[34:35]
	s_add_u32 m0, s28, 0xc00
	s_add_u32 s34, s34, s0
	s_addc_u32 s35, s35, 0
	global_load_lds_dwordx4 v135, s[34:35]
	ds_read_b128 v[168:171], v139 offset:36864
	s_waitcnt lgkmcnt(3)
	v_mfma_f32_32x32x16_bf16 v[52:67], v[160:163], v[148:151], v[52:67]
	s_add_u32 m0, s28, 0x4000
	s_nop 0
	global_load_lds_dwordx4 v136, s[100:101]
	s_add_u32 m0, s28, 0x4400
	s_add_u32 s34, s100, 0x2000
	s_addc_u32 s35, s101, 0
	global_load_lds_dwordx4 v137, s[34:35]
	ds_read_b128 v[176:179], v143 offset:43072
	v_mfma_f32_32x32x16_bf16 v[20:35], v[160:163], v[152:155], v[20:35]
	s_add_u32 m0, s28, 0x4800
	s_add_u32 s34, s100, 0x4000
	s_addc_u32 s35, s101, 0
	global_load_lds_dwordx4 v136, s[34:35]
	s_add_u32 m0, s28, 0x4c00
	s_add_u32 s34, s100, 0x6000
	s_addc_u32 s35, s101, 0
	global_load_lds_dwordx4 v137, s[34:35]
	s_waitcnt lgkmcnt(2)
	v_mfma_f32_32x32x16_bf16 v[84:99], v[172:175], v[164:167], v[84:99]
	s_add_u32 s98, s98, 0x80
	s_addc_u32 s99, s99, 0
	s_add_u32 s100, s100, 0x80
	s_addc_u32 s101, s101, 0
	ds_read_b128 v[188:191], v144 offset:38976
	ds_read_b128 v[180:183], v140 offset:32768
	s_waitcnt lgkmcnt(3)
	v_mfma_f32_32x32x16_bf16 v[36:51], v[172:175], v[168:171], v[36:51]
	ds_read_b128 v[184:187], v140 offset:36864
	s_waitcnt lgkmcnt(3)
	v_mfma_f32_32x32x16_bf16 v[52:67], v[176:179], v[164:167], v[52:67]
	ds_read_b128 v[210:213], v144 offset:43072
	v_mfma_f32_32x32x16_bf16 v[20:35], v[176:179], v[168:171], v[20:35]
	s_waitcnt lgkmcnt(2)
	v_mfma_f32_32x32x16_bf16 v[84:99], v[188:191], v[180:183], v[84:99]
	ds_read_b128 v[156:159], v145 offset:38976
	ds_read_b128 v[148:151], v141 offset:32768
	s_waitcnt lgkmcnt(3)
	v_mfma_f32_32x32x16_bf16 v[36:51], v[188:191], v[184:187], v[36:51]
	ds_read_b128 v[152:155], v141 offset:36864
	s_waitcnt lgkmcnt(3)
	v_mfma_f32_32x32x16_bf16 v[52:67], v[210:213], v[180:183], v[52:67]
	ds_read_b128 v[160:163], v145 offset:43072
	v_mfma_f32_32x32x16_bf16 v[20:35], v[210:213], v[184:187], v[20:35]
	s_waitcnt lgkmcnt(2)
	v_mfma_f32_32x32x16_bf16 v[84:99], v[156:159], v[148:151], v[84:99]
	s_waitcnt lgkmcnt(1)
	v_mfma_f32_32x32x16_bf16 v[36:51], v[156:159], v[152:155], v[36:51]
	s_waitcnt lgkmcnt(0)
	v_mfma_f32_32x32x16_bf16 v[52:67], v[160:163], v[148:151], v[52:67]
	v_mfma_f32_32x32x16_bf16 v[20:35], v[160:163], v[152:155], v[20:35]
	s_branch .Lmbk_next

; DEV int bid_() { int b = blockIdx.x; asm volatile("" : "+s"(b)); return b; }
; template <int NI, bool DEEP = true>
; DEV void gemm_tile(f32x16 (&acc)[2][NI], const bf16* __restrict__ A, int lda, const bf16* __restrict__ Bt, int ldb,
;                    int K, bf16* sA, bf16* sB) {
;     ...
;   int lr = tid >> 3, lc = (tid & 7) * 8;
;   const bf16* Ap = A + (size_t)lr * lda + lc;
;   const bf16* Bp = Bt + (size_t)lr * ldb + lc;
;   u32x4 ra0[4], rb0[2 * NI], ra1[4], rb1[2 * NI];
;     ...
;   G_LOAD(ra0, rb0, 0)
;   if (DEEP) {
;     if (64 < K) G_LOAD(ra1, rb1, 64)
;     for (int k0 = 0; k0 < K; k0 += 128) {
;       G_STEP(ra0, rb0, k0 + 128)
;       if (k0 + 64 < K) G_STEP(ra1, rb1, k0 + 192)
;     }
; __device__ void phase_out(PRef p, int l, const bf16* M, const float* xl, const float* xc, bf16* sA, bf16* sB) {
;     ...
;   for (int t = bid_() >> 3; t < 36 * 8; t += per_) {
;     int rt = xcd_ + 8 * (t / 8), ct = t % 8;
;     if (skip_rt(l, rt)) continue;
;     f32x16 acc[2][2];
;     zero_acc<2>(acc);
;     gemm_tile<2>(acc, M + (size_t)rt * 128 * 1024, 1024, p.WOUT + (size_t)ct * 128 * 1024, 1024, 1024, sA, sB);
.Lout_ptr:
	s_add_u32 s14, s14, s15
	s_lshl_b32 s16, s14, 12
	s_lshl_b32 s14, s20, 9
	s_add_u32 s16, s16, s14
	s_add_u32 s30, s30, s16
	s_addc_u32 s31, s31, 0
	s_add_u32 s26, s26, s16
	s_addc_u32 s27, s27, 0
	v_lshrrev_b32_e32 v242, 4, v196
	v_and_b32_e32 v243, 15, v196
	v_lshlrev_b32_e32 v242, 12, v242
	v_lshl_add_u32 v242, v243, 5, v242
	v_and_b32_e32 v0, 63, v196
	v_lshrrev_b32_e32 v1, 6, v196
	v_lshrrev_b32_e32 v2, 3, v0
	v_readfirstlane_b32 s16, v1
	v_lshrrev_b32_e32 v78, 1, v2
	v_and_b32_e32 v79, 7, v0
	v_xor_b32_e32 v78, v79, v78
	v_lshlrev_b32_e32 v78, 4, v78
	v_lshl_or_b32 v68, v2, 11, v78
	v_xor_b32_e32 v69, 64, v68
	v_lshrrev_b32_e32 v78, 5, v0
	v_bfe_u32 v79, v0, 1, 3
	v_and_b32_e32 v2, 31, v0
	v_lshrrev_b32_e32 v0, 1, v1
	v_and_b32_e32 v1, 1, v1
	v_lshl_add_u32 v0, v0, 6, v2
	v_lshl_add_u32 v1, v1, 6, v2
	v_lshlrev_b32_e32 v0, 7, v0
	v_lshlrev_b32_e32 v1, 7, v1
	v_add_u32_e32 v1, 0x4000, v1
	v_add_u32_e32 v2, 0, v78
	v_xor_b32_e32 v2, v2, v79
	v_lshl_add_u32 v70, v2, 4, v0
	v_lshl_add_u32 v74, v2, 4, v1
	v_add_u32_e32 v2, 2, v78
	v_xor_b32_e32 v2, v2, v79
	v_lshl_add_u32 v71, v2, 4, v0
	v_lshl_add_u32 v75, v2, 4, v1
	v_add_u32_e32 v2, 4, v78
	v_xor_b32_e32 v2, v2, v79
	v_lshl_add_u32 v72, v2, 4, v0
	v_lshl_add_u32 v76, v2, 4, v1
	v_add_u32_e32 v2, 6, v78
	v_xor_b32_e32 v2, v2, v79
	v_lshl_add_u32 v73, v2, 4, v0
	v_lshl_add_u32 v77, v2, 4, v1
	s_lshl_b32 s17, s16, 16
	s_lshl_b32 s16, s16, 12
	s_add_u32 s98, s98, s17
	s_addc_u32 s99, s99, 0
	s_add_u32 s100, s100, s17
	s_addc_u32 s101, s101, 0
	s_waitcnt lgkmcnt(0)
	s_barrier
	s_add_u32 m0, s16, 0x0
	s_nop 0
	global_load_lds_dwordx4 v68, s[98:99]
	s_add_u32 m0, s16, 0x400
	s_add_u32 s14, s98, 0x4000
	s_addc_u32 s15, s99, 0
	global_load_lds_dwordx4 v69, s[14:15]
	s_add_u32 m0, s16, 0x800
	s_add_u32 s14, s98, 0x8000
	s_addc_u32 s15, s99, 0
	global_load_lds_dwordx4 v68, s[14:15]
	s_add_u32 m0, s16, 0xc00
	s_add_u32 s14, s98, 0xc000
	s_addc_u32 s15, s99, 0
	global_load_lds_dwordx4 v69, s[14:15]
	s_add_u32 m0, s16, 0x4000
	s_nop 0
	global_load_lds_dwordx4 v68, s[100:101]
	s_add_u32 m0, s16, 0x4400
	s_add_u32 s14, s100, 0x4000
	s_addc_u32 s15, s101, 0
	global_load_lds_dwordx4 v69, s[14:15]
	s_add_u32 m0, s16, 0x4800
	s_add_u32 s14, s100, 0x8000
	s_addc_u32 s15, s101, 0
	global_load_lds_dwordx4 v68, s[14:15]
	s_add_u32 m0, s16, 0x4c00
	s_add_u32 s14, s100, 0xc000
	s_addc_u32 s15, s101, 0
	global_load_lds_dwordx4 v69, s[14:15]
	s_add_u32 s98, s98, 0x80
	s_addc_u32 s99, s99, 0
	s_add_u32 s100, s100, 0x80
	s_addc_u32 s101, s101, 0
	v_mov_b32_e32 v4, 0
	v_mov_b32_e32 v5, 0
	v_mov_b32_e32 v6, 0
	v_mov_b32_e32 v7, 0
	v_mov_b32_e32 v8, 0
	v_mov_b32_e32 v9, 0
	v_mov_b32_e32 v10, 0
	v_mov_b32_e32 v11, 0
	v_mov_b32_e32 v12, 0
	v_mov_b32_e32 v13, 0
	v_mov_b32_e32 v14, 0
	v_mov_b32_e32 v15, 0
	v_mov_b32_e32 v16, 0
	v_mov_b32_e32 v17, 0
	v_mov_b32_e32 v18, 0
	v_mov_b32_e32 v19, 0
	v_mov_b32_e32 v20, 0
	v_mov_b32_e32 v21, 0
	v_mov_b32_e32 v22, 0
	v_mov_b32_e32 v23, 0
	v_mov_b32_e32 v24, 0
	v_mov_b32_e32 v25, 0
	v_mov_b32_e32 v26, 0
	v_mov_b32_e32 v27, 0
	v_mov_b32_e32 v28, 0
	v_mov_b32_e32 v29, 0
	v_mov_b32_e32 v30, 0
	v_mov_b32_e32 v31, 0
	v_mov_b32_e32 v32, 0
	v_mov_b32_e32 v33, 0
	v_mov_b32_e32 v34, 0
	v_mov_b32_e32 v35, 0
	v_mov_b32_e32 v36, 0
	v_mov_b32_e32 v37, 0
	v_mov_b32_e32 v38, 0
	v_mov_b32_e32 v39, 0
	v_mov_b32_e32 v40, 0
	v_mov_b32_e32 v41, 0
	v_mov_b32_e32 v42, 0
	v_mov_b32_e32 v43, 0
	v_mov_b32_e32 v44, 0
	v_mov_b32_e32 v45, 0
	v_mov_b32_e32 v46, 0
	v_mov_b32_e32 v47, 0
	v_mov_b32_e32 v48, 0
	v_mov_b32_e32 v49, 0
	v_mov_b32_e32 v50, 0
	v_mov_b32_e32 v51, 0
	v_mov_b32_e32 v52, 0
	v_mov_b32_e32 v53, 0
	v_mov_b32_e32 v54, 0
	v_mov_b32_e32 v55, 0
	v_mov_b32_e32 v56, 0
	v_mov_b32_e32 v57, 0
	v_mov_b32_e32 v58, 0
	v_mov_b32_e32 v59, 0
	v_mov_b32_e32 v60, 0
	v_mov_b32_e32 v61, 0
	v_mov_b32_e32 v62, 0
	v_mov_b32_e32 v63, 0
	v_mov_b32_e32 v64, 0
	v_mov_b32_e32 v65, 0
	v_mov_b32_e32 v66, 0
	v_mov_b32_e32 v67, 0
	s_waitcnt vmcnt(0)
	s_barrier
	ds_read_b128 v[88:91], v74 offset:0
	ds_read_b128 v[80:83], v70 offset:0
	ds_read_b128 v[84:87], v70 offset:4096
	ds_read_b128 v[92:95], v74 offset:4096
	s_waitcnt lgkmcnt(2)
	v_mfma_f32_32x32x16_bf16 v[52:67], v[88:91], v[80:83], v[52:67]
	s_add_u32 m0, s16, 0x8000
	s_nop 0
	global_load_lds_dwordx4 v68, s[98:99]
	s_add_u32 m0, s16, 0x8400
	s_add_u32 s14, s98, 0x4000
	s_addc_u32 s15, s99, 0
	global_load_lds_dwordx4 v69, s[14:15]
	ds_read_b128 v[104:107], v75 offset:0
	ds_read_b128 v[96:99], v71 offset:0
	s_waitcnt lgkmcnt(3)
	v_mfma_f32_32x32x16_bf16 v[20:35], v[88:91], v[84:87], v[20:35]
	s_add_u32 m0, s16, 0x8800
	s_add_u32 s14, s98, 0x8000
	s_addc_u32 s15, s99, 0
	global_load_lds_dwordx4 v68, s[14:15]
	s_add_u32 m0, s16, 0x8c00
	s_add_u32 s14, s98, 0xc000
	s_addc_u32 s15, s99, 0
	global_load_lds_dwordx4 v69, s[14:15]
	ds_read_b128 v[100:103], v71 offset:4096
	s_waitcnt lgkmcnt(3)
	v_mfma_f32_32x32x16_bf16 v[36:51], v[92:95], v[80:83], v[36:51]
	s_add_u32 m0, s16, 0xd840
	s_nop 0
	global_load_lds_dwordx4 v68, s[100:101]
	s_add_u32 m0, s16, 0xdc40
	s_add_u32 s14, s100, 0x4000
	s_addc_u32 s15, s101, 0
	global_load_lds_dwordx4 v69, s[14:15]
	ds_read_b128 v[108:111], v75 offset:4096
	v_mfma_f32_32x32x16_bf16 v[4:19], v[92:95], v[84:87], v[4:19]
	s_add_u32 m0, s16, 0xe040
	s_add_u32 s14, s100, 0x8000
	s_addc_u32 s15, s101, 0
	global_load_lds_dwordx4 v68, s[14:15]
	s_add_u32 m0, s16, 0xe440
	s_add_u32 s14, s100, 0xc000
	s_addc_u32 s15, s101, 0
	global_load_lds_dwordx4 v69, s[14:15]
	s_waitcnt lgkmcnt(2)
	v_mfma_f32_32x32x16_bf16 v[52:67], v[104:107], v[96:99], v[52:67]
	s_add_u32 s98, s98, 0x80
	s_addc_u32 s99, s99, 0
	s_add_u32 s100, s100, 0x80
	s_addc_u32 s101, s101, 0
	global_load_dwordx4 v[162:165], v242, s[30:31]
	ds_read_b128 v[120:123], v76 offset:0
	ds_read_b128 v[112:115], v72 offset:0
	s_waitcnt lgkmcnt(3)
	v_mfma_f32_32x32x16_bf16 v[20:35], v[104:107], v[100:103], v[20:35]
	ds_read_b128 v[116:119], v72 offset:4096
	s_waitcnt lgkmcnt(3)
	v_mfma_f32_32x32x16_bf16 v[36:51], v[108:111], v[96:99], v[36:51]
	ds_read_b128 v[124:127], v76 offset:4096
	v_mfma_f32_32x32x16_bf16 v[4:19], v[108:111], v[100:103], v[4:19]
	s_waitcnt lgkmcnt(2)
	v_mfma_f32_32x32x16_bf16 v[52:67], v[120:123], v[112:115], v[52:67]
	ds_read_b128 v[88:91], v77 offset:0
	ds_read_b128 v[80:83], v73 offset:0
	s_waitcnt lgkmcnt(3)
	v_mfma_f32_32x32x16_bf16 v[20:35], v[120:123], v[116:119], v[20:35]
	ds_read_b128 v[84:87], v73 offset:4096
	s_waitcnt lgkmcnt(3)
	v_mfma_f32_32x32x16_bf16 v[36:51], v[124:127], v[112:115], v[36:51]
	ds_read_b128 v[92:95], v77 offset:4096
	v_mfma_f32_32x32x16_bf16 v[4:19], v[124:127], v[116:119], v[4:19]
	s_waitcnt lgkmcnt(2)
	v_mfma_f32_32x32x16_bf16 v[52:67], v[88:91], v[80:83], v[52:67]
	s_waitcnt lgkmcnt(1)
	v_mfma_f32_32x32x16_bf16 v[20:35], v[88:91], v[84:87], v[20:35]
	s_waitcnt lgkmcnt(0)
	v_mfma_f32_32x32x16_bf16 v[36:51], v[92:95], v[80:83], v[36:51]
	v_mfma_f32_32x32x16_bf16 v[4:19], v[92:95], v[84:87], v[4:19]
	s_waitcnt vmcnt(1)
	s_barrier
; template <int NI, bool DEEP = true>
; DEV void gemm_tile(f32x16 (&acc)[2][NI], const bf16* __restrict__ A, int lda, const bf16* __restrict__ Bt, int ldb,
;                    int K, bf16* sA, bf16* sB) {
;     ...
;   G_LOAD(ra0, rb0, 0)
;   if (DEEP) {
;     if (64 < K) G_LOAD(ra1, rb1, 64)
;     for (int k0 = 0; k0 < K; k0 += 128) {
;       G_STEP(ra0, rb0, k0 + 128)
;       if (k0 + 64 < K) G_STEP(ra1, rb1, k0 + 192)
;     }
	ds_read_b128 v[88:91], v74 offset:38976
	ds_read_b128 v[80:83], v70 offset:32768
	ds_read_b128 v[84:87], v70 offset:36864
	ds_read_b128 v[92:95], v74 offset:43072
	s_waitcnt lgkmcnt(2)
	v_mfma_f32_32x32x16_bf16 v[52:67], v[88:91], v[80:83], v[52:67]
	s_add_u32 m0, s16, 0x0
	s_nop 0
	global_load_lds_dwordx4 v68, s[98:99]
	s_add_u32 m0, s16, 0x400
	s_add_u32 s14, s98, 0x4000
	s_addc_u32 s15, s99, 0
	global_load_lds_dwordx4 v69, s[14:15]
	ds_read_b128 v[104:107], v75 offset:38976
	ds_read_b128 v[96:99], v71 offset:32768
	s_waitcnt lgkmcnt(3)
	v_mfma_f32_32x32x16_bf16 v[20:35], v[88:91], v[84:87], v[20:35]
	s_add_u32 m0, s16, 0x800
	s_add_u32 s14, s98, 0x8000
	s_addc_u32 s15, s99, 0
	global_load_lds_dwordx4 v68, s[14:15]
	s_add_u32 m0, s16, 0xc00
	s_add_u32 s14, s98, 0xc000
	s_addc_u32 s15, s99, 0
	global_load_lds_dwordx4 v69, s[14:15]
	ds_read_b128 v[100:103], v71 offset:36864
	s_waitcnt lgkmcnt(3)
	v_mfma_f32_32x32x16_bf16 v[36:51], v[92:95], v[80:83], v[36:51]
	s_add_u32 m0, s16, 0x4000
	s_nop 0
	global_load_lds_dwordx4 v68, s[100:101]
	s_add_u32 m0, s16, 0x4400
	s_add_u32 s14, s100, 0x4000
	s_addc_u32 s15, s101, 0
	global_load_lds_dwordx4 v69, s[14:15]
	ds_read_b128 v[108:111], v75 offset:43072
	v_mfma_f32_32x32x16_bf16 v[4:19], v[92:95], v[84:87], v[4:19]
	s_add_u32 m0, s16, 0x4800
	s_add_u32 s14, s100, 0x8000
	s_addc_u32 s15, s101, 0
	global_load_lds_dwordx4 v68, s[14:15]
	s_add_u32 m0, s16, 0x4c00
	s_add_u32 s14, s100, 0xc000
	s_addc_u32 s15, s101, 0
	global_load_lds_dwordx4 v69, s[14:15]
	s_waitcnt lgkmcnt(2)
	v_mfma_f32_32x32x16_bf16 v[52:67], v[104:107], v[96:99], v[52:67]
	s_add_u32 s98, s98, 0x80
	s_addc_u32 s99, s99, 0
	s_add_u32 s100, s100, 0x80
	s_addc_u32 s101, s101, 0
	global_load_dwordx4 v[166:169], v242, s[30:31] offset:16
	s_add_u32 s30, s30, 0x10000
	s_addc_u32 s31, s31, 0
	ds_read_b128 v[120:123], v76 offset:38976
	ds_read_b128 v[112:115], v72 offset:32768
	s_waitcnt lgkmcnt(3)
	v_mfma_f32_32x32x16_bf16 v[20:35], v[104:107], v[100:103], v[20:35]
	ds_read_b128 v[116:119], v72 offset:36864
	s_waitcnt lgkmcnt(3)
	v_mfma_f32_32x32x16_bf16 v[36:51], v[108:111], v[96:99], v[36:51]
	ds_read_b128 v[124:127], v76 offset:43072
	v_mfma_f32_32x32x16_bf16 v[4:19], v[108:111], v[100:103], v[4:19]
	s_waitcnt lgkmcnt(2)
	v_mfma_f32_32x32x16_bf16 v[52:67], v[120:123], v[112:115], v[52:67]
	ds_read_b128 v[88:91], v77 offset:38976
	ds_read_b128 v[80:83], v73 offset:32768
	s_waitcnt lgkmcnt(3)
	v_mfma_f32_32x32x16_bf16 v[20:35], v[120:123], v[116:119], v[20:35]
	ds_read_b128 v[84:87], v73 offset:36864
	s_waitcnt lgkmcnt(3)
	v_mfma_f32_32x32x16_bf16 v[36:51], v[124:127], v[112:115], v[36:51]
	ds_read_b128 v[92:95], v77 offset:43072
	v_mfma_f32_32x32x16_bf16 v[4:19], v[124:127], v[116:119], v[4:19]
	s_waitcnt lgkmcnt(2)
	v_mfma_f32_32x32x16_bf16 v[52:67], v[88:91], v[80:83], v[52:67]
	s_waitcnt lgkmcnt(1)
	v_mfma_f32_32x32x16_bf16 v[20:35], v[88:91], v[84:87], v[20:35]
	s_waitcnt lgkmcnt(0)
	v_mfma_f32_32x32x16_bf16 v[36:51], v[92:95], v[80:83], v[36:51]
	v_mfma_f32_32x32x16_bf16 v[4:19], v[92:95], v[84:87], v[4:19]
	s_waitcnt vmcnt(1)
	s_barrier
	ds_read_b128 v[88:91], v74 offset:0
	ds_read_b128 v[80:83], v70 offset:0
	ds_read_b128 v[84:87], v70 offset:4096
	ds_read_b128 v[92:95], v74 offset:4096
	s_waitcnt lgkmcnt(2)
	v_mfma_f32_32x32x16_bf16 v[52:67], v[88:91], v[80:83], v[52:67]
	s_add_u32 m0, s16, 0x8000
	s_nop 0
	global_load_lds_dwordx4 v68, s[98:99]
	s_add_u32 m0, s16, 0x8400
	s_add_u32 s14, s98, 0x4000
	s_addc_u32 s15, s99, 0
	global_load_lds_dwordx4 v69, s[14:15]
	ds_read_b128 v[104:107], v75 offset:0
	ds_read_b128 v[96:99], v71 offset:0
	s_waitcnt lgkmcnt(3)
	v_mfma_f32_32x32x16_bf16 v[20:35], v[88:91], v[84:87], v[20:35]
	s_add_u32 m0, s16, 0x8800
	s_add_u32 s14, s98, 0x8000
	s_addc_u32 s15, s99, 0
	global_load_lds_dwordx4 v68, s[14:15]
	s_add_u32 m0, s16, 0x8c00
	s_add_u32 s14, s98, 0xc000
	s_addc_u32 s15, s99, 0
	global_load_lds_dwordx4 v69, s[14:15]
	ds_read_b128 v[100:103], v71 offset:4096
	s_waitcnt lgkmcnt(3)
	v_mfma_f32_32x32x16_bf16 v[36:51], v[92:95], v[80:83], v[36:51]
	s_add_u32 m0, s16, 0xd840
	s_nop 0
	global_load_lds_dwordx4 v68, s[100:101]
	s_add_u32 m0, s16, 0xdc40
	s_add_u32 s14, s100, 0x4000
	s_addc_u32 s15, s101, 0
	global_load_lds_dwordx4 v69, s[14:15]
	ds_read_b128 v[108:111], v75 offset:4096
	v_mfma_f32_32x32x16_bf16 v[4:19], v[92:95], v[84:87], v[4:19]
	s_add_u32 m0, s16, 0xe040
	s_add_u32 s14, s100, 0x8000
	s_addc_u32 s15, s101, 0
	global_load_lds_dwordx4 v68, s[14:15]
	s_add_u32 m0, s16, 0xe440
	s_add_u32 s14, s100, 0xc000
	s_addc_u32 s15, s101, 0
	global_load_lds_dwordx4 v69, s[14:15]
	s_waitcnt lgkmcnt(2)
	v_mfma_f32_32x32x16_bf16 v[52:67], v[104:107], v[96:99], v[52:67]
	s_add_u32 s98, s98, 0x80
	s_addc_u32 s99, s99, 0
	s_add_u32 s100, s100, 0x80
	s_addc_u32 s101, s101, 0
	global_load_dwordx4 v[170:173], v242, s[30:31]
	ds_read_b128 v[120:123], v76 offset:0
	ds_read_b128 v[112:115], v72 offset:0
	s_waitcnt lgkmcnt(3)
	v_mfma_f32_32x32x16_bf16 v[20:35], v[104:107], v[100:103], v[20:35]
	ds_read_b128 v[116:119], v72 offset:4096
	s_waitcnt lgkmcnt(3)
	v_mfma_f32_32x32x16_bf16 v[36:51], v[108:111], v[96:99], v[36:51]
	ds_read_b128 v[124:127], v76 offset:4096
	v_mfma_f32_32x32x16_bf16 v[4:19], v[108:111], v[100:103], v[4:19]
	s_waitcnt lgkmcnt(2)
	v_mfma_f32_32x32x16_bf16 v[52:67], v[120:123], v[112:115], v[52:67]
	ds_read_b128 v[88:91], v77 offset:0
	ds_read_b128 v[80:83], v73 offset:0
	s_waitcnt lgkmcnt(3)
	v_mfma_f32_32x32x16_bf16 v[20:35], v[120:123], v[116:119], v[20:35]
	ds_read_b128 v[84:87], v73 offset:4096
	s_waitcnt lgkmcnt(3)
	v_mfma_f32_32x32x16_bf16 v[36:51], v[124:127], v[112:115], v[36:51]
	ds_read_b128 v[92:95], v77 offset:4096
	v_mfma_f32_32x32x16_bf16 v[4:19], v[124:127], v[116:119], v[4:19]
	s_waitcnt lgkmcnt(2)
	v_mfma_f32_32x32x16_bf16 v[52:67], v[88:91], v[80:83], v[52:67]
	s_waitcnt lgkmcnt(1)
	v_mfma_f32_32x32x16_bf16 v[20:35], v[88:91], v[84:87], v[20:35]
	s_waitcnt lgkmcnt(0)
	v_mfma_f32_32x32x16_bf16 v[36:51], v[92:95], v[80:83], v[36:51]
	v_mfma_f32_32x32x16_bf16 v[4:19], v[92:95], v[84:87], v[4:19]
	s_waitcnt vmcnt(1)
	s_barrier
; template <int NI, bool DEEP = true>
; DEV void gemm_tile(f32x16 (&acc)[2][NI], const bf16* __restrict__ A, int lda, const bf16* __restrict__ Bt, int ldb,
;                    int K, bf16* sA, bf16* sB) {
;     ...
;   G_LOAD(ra0, rb0, 0)
;   if (DEEP) {
;     if (64 < K) G_LOAD(ra1, rb1, 64)
;     for (int k0 = 0; k0 < K; k0 += 128) {
;       G_STEP(ra0, rb0, k0 + 128)
;       if (k0 + 64 < K) G_STEP(ra1, rb1, k0 + 192)
;     }
	ds_read_b128 v[88:91], v74 offset:38976
	ds_read_b128 v[80:83], v70 offset:32768
	ds_read_b128 v[84:87], v70 offset:36864
	ds_read_b128 v[92:95], v74 offset:43072
	s_waitcnt lgkmcnt(2)
	v_mfma_f32_32x32x16_bf16 v[52:67], v[88:91], v[80:83], v[52:67]
	s_add_u32 m0, s16, 0x0
	s_nop 0
	global_load_lds_dwordx4 v68, s[98:99]
	s_add_u32 m0, s16, 0x400
	s_add_u32 s14, s98, 0x4000
	s_addc_u32 s15, s99, 0
	global_load_lds_dwordx4 v69, s[14:15]
	ds_read_b128 v[104:107], v75 offset:38976
	ds_read_b128 v[96:99], v71 offset:32768
	s_waitcnt lgkmcnt(3)
	v_mfma_f32_32x32x16_bf16 v[20:35], v[88:91], v[84:87], v[20:35]
	s_add_u32 m0, s16, 0x800
	s_add_u32 s14, s98, 0x8000
	s_addc_u32 s15, s99, 0
	global_load_lds_dwordx4 v68, s[14:15]
	s_add_u32 m0, s16, 0xc00
	s_add_u32 s14, s98, 0xc000
	s_addc_u32 s15, s99, 0
	global_load_lds_dwordx4 v69, s[14:15]
	ds_read_b128 v[100:103], v71 offset:36864
	s_waitcnt lgkmcnt(3)
	v_mfma_f32_32x32x16_bf16 v[36:51], v[92:95], v[80:83], v[36:51]
	s_add_u32 m0, s16, 0x4000
	s_nop 0
	global_load_lds_dwordx4 v68, s[100:101]
	s_add_u32 m0, s16, 0x4400
	s_add_u32 s14, s100, 0x4000
	s_addc_u32 s15, s101, 0
	global_load_lds_dwordx4 v69, s[14:15]
	ds_read_b128 v[108:111], v75 offset:43072
	v_mfma_f32_32x32x16_bf16 v[4:19], v[92:95], v[84:87], v[4:19]
	s_add_u32 m0, s16, 0x4800
	s_add_u32 s14, s100, 0x8000
	s_addc_u32 s15, s101, 0
	global_load_lds_dwordx4 v68, s[14:15]
	s_add_u32 m0, s16, 0x4c00
	s_add_u32 s14, s100, 0xc000
	s_addc_u32 s15, s101, 0
	global_load_lds_dwordx4 v69, s[14:15]
	s_waitcnt lgkmcnt(2)
	v_mfma_f32_32x32x16_bf16 v[52:67], v[104:107], v[96:99], v[52:67]
	s_add_u32 s98, s98, 0x80
	s_addc_u32 s99, s99, 0
	s_add_u32 s100, s100, 0x80
	s_addc_u32 s101, s101, 0
	global_load_dwordx4 v[174:177], v242, s[30:31] offset:16
	s_add_u32 s30, s30, 0x10000
	s_addc_u32 s31, s31, 0
	ds_read_b128 v[120:123], v76 offset:38976
	ds_read_b128 v[112:115], v72 offset:32768
	s_waitcnt lgkmcnt(3)
	v_mfma_f32_32x32x16_bf16 v[20:35], v[104:107], v[100:103], v[20:35]
	ds_read_b128 v[116:119], v72 offset:36864
	s_waitcnt lgkmcnt(3)
	v_mfma_f32_32x32x16_bf16 v[36:51], v[108:111], v[96:99], v[36:51]
	ds_read_b128 v[124:127], v76 offset:43072
	v_mfma_f32_32x32x16_bf16 v[4:19], v[108:111], v[100:103], v[4:19]
	s_waitcnt lgkmcnt(2)
	v_mfma_f32_32x32x16_bf16 v[52:67], v[120:123], v[112:115], v[52:67]
	ds_read_b128 v[88:91], v77 offset:38976
	ds_read_b128 v[80:83], v73 offset:32768
	s_waitcnt lgkmcnt(3)
	v_mfma_f32_32x32x16_bf16 v[20:35], v[120:123], v[116:119], v[20:35]
	ds_read_b128 v[84:87], v73 offset:36864
	s_waitcnt lgkmcnt(3)
	v_mfma_f32_32x32x16_bf16 v[36:51], v[124:127], v[112:115], v[36:51]
	ds_read_b128 v[92:95], v77 offset:43072
	v_mfma_f32_32x32x16_bf16 v[4:19], v[124:127], v[116:119], v[4:19]
	s_waitcnt lgkmcnt(2)
	v_mfma_f32_32x32x16_bf16 v[52:67], v[88:91], v[80:83], v[52:67]
	s_waitcnt lgkmcnt(1)
	v_mfma_f32_32x32x16_bf16 v[20:35], v[88:91], v[84:87], v[20:35]
	s_waitcnt lgkmcnt(0)
	v_mfma_f32_32x32x16_bf16 v[36:51], v[92:95], v[80:83], v[36:51]
	v_mfma_f32_32x32x16_bf16 v[4:19], v[92:95], v[84:87], v[4:19]
	s_waitcnt vmcnt(1)
	s_barrier
	ds_read_b128 v[88:91], v74 offset:0
	ds_read_b128 v[80:83], v70 offset:0
	ds_read_b128 v[84:87], v70 offset:4096
	ds_read_b128 v[92:95], v74 offset:4096
	s_waitcnt lgkmcnt(2)
	v_mfma_f32_32x32x16_bf16 v[52:67], v[88:91], v[80:83], v[52:67]
	s_add_u32 m0, s16, 0x8000
	s_nop 0
	global_load_lds_dwordx4 v68, s[98:99]
	s_add_u32 m0, s16, 0x8400
	s_add_u32 s14, s98, 0x4000
	s_addc_u32 s15, s99, 0
	global_load_lds_dwordx4 v69, s[14:15]
	ds_read_b128 v[104:107], v75 offset:0
	ds_read_b128 v[96:99], v71 offset:0
	s_waitcnt lgkmcnt(3)
	v_mfma_f32_32x32x16_bf16 v[20:35], v[88:91], v[84:87], v[20:35]
	s_add_u32 m0, s16, 0x8800
	s_add_u32 s14, s98, 0x8000
	s_addc_u32 s15, s99, 0
	global_load_lds_dwordx4 v68, s[14:15]
	s_add_u32 m0, s16, 0x8c00
	s_add_u32 s14, s98, 0xc000
	s_addc_u32 s15, s99, 0
	global_load_lds_dwordx4 v69, s[14:15]
	ds_read_b128 v[100:103], v71 offset:4096
	s_waitcnt lgkmcnt(3)
	v_mfma_f32_32x32x16_bf16 v[36:51], v[92:95], v[80:83], v[36:51]
	s_add_u32 m0, s16, 0xd840
	s_nop 0
	global_load_lds_dwordx4 v68, s[100:101]
	s_add_u32 m0, s16, 0xdc40
	s_add_u32 s14, s100, 0x4000
	s_addc_u32 s15, s101, 0
	global_load_lds_dwordx4 v69, s[14:15]
	ds_read_b128 v[108:111], v75 offset:4096
	v_mfma_f32_32x32x16_bf16 v[4:19], v[92:95], v[84:87], v[4:19]
	s_add_u32 m0, s16, 0xe040
	s_add_u32 s14, s100, 0x8000
	s_addc_u32 s15, s101, 0
	global_load_lds_dwordx4 v68, s[14:15]
	s_add_u32 m0, s16, 0xe440
	s_add_u32 s14, s100, 0xc000
	s_addc_u32 s15, s101, 0
	global_load_lds_dwordx4 v69, s[14:15]
	s_waitcnt lgkmcnt(2)
	v_mfma_f32_32x32x16_bf16 v[52:67], v[104:107], v[96:99], v[52:67]
	s_add_u32 s98, s98, 0x80
	s_addc_u32 s99, s99, 0
	s_add_u32 s100, s100, 0x80
	s_addc_u32 s101, s101, 0
	global_load_dwordx4 v[178:181], v242, s[30:31]
	ds_read_b128 v[120:123], v76 offset:0
	ds_read_b128 v[112:115], v72 offset:0
	s_waitcnt lgkmcnt(3)
	v_mfma_f32_32x32x16_bf16 v[20:35], v[104:107], v[100:103], v[20:35]
	ds_read_b128 v[116:119], v72 offset:4096
	s_waitcnt lgkmcnt(3)
	v_mfma_f32_32x32x16_bf16 v[36:51], v[108:111], v[96:99], v[36:51]
	ds_read_b128 v[124:127], v76 offset:4096
	v_mfma_f32_32x32x16_bf16 v[4:19], v[108:111], v[100:103], v[4:19]
	s_waitcnt lgkmcnt(2)
	v_mfma_f32_32x32x16_bf16 v[52:67], v[120:123], v[112:115], v[52:67]
	ds_read_b128 v[88:91], v77 offset:0
	ds_read_b128 v[80:83], v73 offset:0
	s_waitcnt lgkmcnt(3)
	v_mfma_f32_32x32x16_bf16 v[20:35], v[120:123], v[116:119], v[20:35]
	ds_read_b128 v[84:87], v73 offset:4096
	s_waitcnt lgkmcnt(3)
	v_mfma_f32_32x32x16_bf16 v[36:51], v[124:127], v[112:115], v[36:51]
	ds_read_b128 v[92:95], v77 offset:4096
	v_mfma_f32_32x32x16_bf16 v[4:19], v[124:127], v[116:119], v[4:19]
	s_waitcnt lgkmcnt(2)
	v_mfma_f32_32x32x16_bf16 v[52:67], v[88:91], v[80:83], v[52:67]
	s_waitcnt lgkmcnt(1)
	v_mfma_f32_32x32x16_bf16 v[20:35], v[88:91], v[84:87], v[20:35]
	s_waitcnt lgkmcnt(0)
	v_mfma_f32_32x32x16_bf16 v[36:51], v[92:95], v[80:83], v[36:51]
	v_mfma_f32_32x32x16_bf16 v[4:19], v[92:95], v[84:87], v[4:19]
	s_waitcnt vmcnt(1)
	s_barrier
; template <int NI, bool DEEP = true>
; DEV void gemm_tile(f32x16 (&acc)[2][NI], const bf16* __restrict__ A, int lda, const bf16* __restrict__ Bt, int ldb,
;                    int K, bf16* sA, bf16* sB) {
;     ...
;   G_LOAD(ra0, rb0, 0)
;   if (DEEP) {
;     if (64 < K) G_LOAD(ra1, rb1, 64)
;     for (int k0 = 0; k0 < K; k0 += 128) {
;       G_STEP(ra0, rb0, k0 + 128)
;       if (k0 + 64 < K) G_STEP(ra1, rb1, k0 + 192)
;     }
	ds_read_b128 v[88:91], v74 offset:38976
	ds_read_b128 v[80:83], v70 offset:32768
	ds_read_b128 v[84:87], v70 offset:36864
	ds_read_b128 v[92:95], v74 offset:43072
	s_waitcnt lgkmcnt(2)
	v_mfma_f32_32x32x16_bf16 v[52:67], v[88:91], v[80:83], v[52:67]
	s_add_u32 m0, s16, 0x0
	s_nop 0
	global_load_lds_dwordx4 v68, s[98:99]
	s_add_u32 m0, s16, 0x400
	s_add_u32 s14, s98, 0x4000
	s_addc_u32 s15, s99, 0
	global_load_lds_dwordx4 v69, s[14:15]
	ds_read_b128 v[104:107], v75 offset:38976
	ds_read_b128 v[96:99], v71 offset:32768
	s_waitcnt lgkmcnt(3)
	v_mfma_f32_32x32x16_bf16 v[20:35], v[88:91], v[84:87], v[20:35]
	s_add_u32 m0, s16, 0x800
	s_add_u32 s14, s98, 0x8000
	s_addc_u32 s15, s99, 0
	global_load_lds_dwordx4 v68, s[14:15]
	s_add_u32 m0, s16, 0xc00
	s_add_u32 s14, s98, 0xc000
	s_addc_u32 s15, s99, 0
	global_load_lds_dwordx4 v69, s[14:15]
	ds_read_b128 v[100:103], v71 offset:36864
	s_waitcnt lgkmcnt(3)
	v_mfma_f32_32x32x16_bf16 v[36:51], v[92:95], v[80:83], v[36:51]
	s_add_u32 m0, s16, 0x4000
	s_nop 0
	global_load_lds_dwordx4 v68, s[100:101]
	s_add_u32 m0, s16, 0x4400
	s_add_u32 s14, s100, 0x4000
	s_addc_u32 s15, s101, 0
	global_load_lds_dwordx4 v69, s[14:15]
	ds_read_b128 v[108:111], v75 offset:43072
	v_mfma_f32_32x32x16_bf16 v[4:19], v[92:95], v[84:87], v[4:19]
	s_add_u32 m0, s16, 0x4800
	s_add_u32 s14, s100, 0x8000
	s_addc_u32 s15, s101, 0
	global_load_lds_dwordx4 v68, s[14:15]
	s_add_u32 m0, s16, 0x4c00
	s_add_u32 s14, s100, 0xc000
	s_addc_u32 s15, s101, 0
	global_load_lds_dwordx4 v69, s[14:15]
	s_waitcnt lgkmcnt(2)
	v_mfma_f32_32x32x16_bf16 v[52:67], v[104:107], v[96:99], v[52:67]
	s_add_u32 s98, s98, 0x80
	s_addc_u32 s99, s99, 0
	s_add_u32 s100, s100, 0x80
	s_addc_u32 s101, s101, 0
	global_load_dwordx4 v[182:185], v242, s[30:31] offset:16
	s_add_u32 s30, s30, 0x10000
	s_addc_u32 s31, s31, 0
	ds_read_b128 v[120:123], v76 offset:38976
	ds_read_b128 v[112:115], v72 offset:32768
	s_waitcnt lgkmcnt(3)
	v_mfma_f32_32x32x16_bf16 v[20:35], v[104:107], v[100:103], v[20:35]
	ds_read_b128 v[116:119], v72 offset:36864
	s_waitcnt lgkmcnt(3)
	v_mfma_f32_32x32x16_bf16 v[36:51], v[108:111], v[96:99], v[36:51]
	ds_read_b128 v[124:127], v76 offset:43072
	v_mfma_f32_32x32x16_bf16 v[4:19], v[108:111], v[100:103], v[4:19]
	s_waitcnt lgkmcnt(2)
	v_mfma_f32_32x32x16_bf16 v[52:67], v[120:123], v[112:115], v[52:67]
	ds_read_b128 v[88:91], v77 offset:38976
	ds_read_b128 v[80:83], v73 offset:32768
	s_waitcnt lgkmcnt(3)
	v_mfma_f32_32x32x16_bf16 v[20:35], v[120:123], v[116:119], v[20:35]
	ds_read_b128 v[84:87], v73 offset:36864
	s_waitcnt lgkmcnt(3)
	v_mfma_f32_32x32x16_bf16 v[36:51], v[124:127], v[112:115], v[36:51]
	ds_read_b128 v[92:95], v77 offset:43072
	v_mfma_f32_32x32x16_bf16 v[4:19], v[124:127], v[116:119], v[4:19]
	s_waitcnt lgkmcnt(2)
	v_mfma_f32_32x32x16_bf16 v[52:67], v[88:91], v[80:83], v[52:67]
	s_waitcnt lgkmcnt(1)
	v_mfma_f32_32x32x16_bf16 v[20:35], v[88:91], v[84:87], v[20:35]
	s_waitcnt lgkmcnt(0)
	v_mfma_f32_32x32x16_bf16 v[36:51], v[92:95], v[80:83], v[36:51]
	v_mfma_f32_32x32x16_bf16 v[4:19], v[92:95], v[84:87], v[4:19]
	s_waitcnt vmcnt(1)
	s_barrier
	ds_read_b128 v[88:91], v74 offset:0
	ds_read_b128 v[80:83], v70 offset:0
	ds_read_b128 v[84:87], v70 offset:4096
	ds_read_b128 v[92:95], v74 offset:4096
	s_waitcnt lgkmcnt(2)
	v_mfma_f32_32x32x16_bf16 v[52:67], v[88:91], v[80:83], v[52:67]
	s_add_u32 m0, s16, 0x8000
	s_nop 0
	global_load_lds_dwordx4 v68, s[98:99]
	s_add_u32 m0, s16, 0x8400
	s_add_u32 s14, s98, 0x4000
	s_addc_u32 s15, s99, 0
	global_load_lds_dwordx4 v69, s[14:15]
	ds_read_b128 v[104:107], v75 offset:0
	ds_read_b128 v[96:99], v71 offset:0
	s_waitcnt lgkmcnt(3)
	v_mfma_f32_32x32x16_bf16 v[20:35], v[88:91], v[84:87], v[20:35]
	s_add_u32 m0, s16, 0x8800
	s_add_u32 s14, s98, 0x8000
	s_addc_u32 s15, s99, 0
	global_load_lds_dwordx4 v68, s[14:15]
	s_add_u32 m0, s16, 0x8c00
	s_add_u32 s14, s98, 0xc000
	s_addc_u32 s15, s99, 0
	global_load_lds_dwordx4 v69, s[14:15]
	ds_read_b128 v[100:103], v71 offset:4096
	s_waitcnt lgkmcnt(3)
	v_mfma_f32_32x32x16_bf16 v[36:51], v[92:95], v[80:83], v[36:51]
	s_add_u32 m0, s16, 0xd840
	s_nop 0
	global_load_lds_dwordx4 v68, s[100:101]
	s_add_u32 m0, s16, 0xdc40
	s_add_u32 s14, s100, 0x4000
	s_addc_u32 s15, s101, 0
	global_load_lds_dwordx4 v69, s[14:15]
	ds_read_b128 v[108:111], v75 offset:4096
	v_mfma_f32_32x32x16_bf16 v[4:19], v[92:95], v[84:87], v[4:19]
	s_add_u32 m0, s16, 0xe040
	s_add_u32 s14, s100, 0x8000
	s_addc_u32 s15, s101, 0
	global_load_lds_dwordx4 v68, s[14:15]
	s_add_u32 m0, s16, 0xe440
	s_add_u32 s14, s100, 0xc000
	s_addc_u32 s15, s101, 0
	global_load_lds_dwordx4 v69, s[14:15]
	s_waitcnt lgkmcnt(2)
	v_mfma_f32_32x32x16_bf16 v[52:67], v[104:107], v[96:99], v[52:67]
	s_add_u32 s98, s98, 0x80
	s_addc_u32 s99, s99, 0
	s_add_u32 s100, s100, 0x80
	s_addc_u32 s101, s101, 0
	global_load_dwordx4 v[186:189], v242, s[30:31]
	ds_read_b128 v[120:123], v76 offset:0
	ds_read_b128 v[112:115], v72 offset:0
	s_waitcnt lgkmcnt(3)
	v_mfma_f32_32x32x16_bf16 v[20:35], v[104:107], v[100:103], v[20:35]
	ds_read_b128 v[116:119], v72 offset:4096
	s_waitcnt lgkmcnt(3)
	v_mfma_f32_32x32x16_bf16 v[36:51], v[108:111], v[96:99], v[36:51]
	ds_read_b128 v[124:127], v76 offset:4096
	v_mfma_f32_32x32x16_bf16 v[4:19], v[108:111], v[100:103], v[4:19]
	s_waitcnt lgkmcnt(2)
	v_mfma_f32_32x32x16_bf16 v[52:67], v[120:123], v[112:115], v[52:67]
	ds_read_b128 v[88:91], v77 offset:0
	ds_read_b128 v[80:83], v73 offset:0
	s_waitcnt lgkmcnt(3)
	v_mfma_f32_32x32x16_bf16 v[20:35], v[120:123], v[116:119], v[20:35]
	ds_read_b128 v[84:87], v73 offset:4096
	s_waitcnt lgkmcnt(3)
	v_mfma_f32_32x32x16_bf16 v[36:51], v[124:127], v[112:115], v[36:51]
	ds_read_b128 v[92:95], v77 offset:4096
	v_mfma_f32_32x32x16_bf16 v[4:19], v[124:127], v[116:119], v[4:19]
	s_waitcnt lgkmcnt(2)
	v_mfma_f32_32x32x16_bf16 v[52:67], v[88:91], v[80:83], v[52:67]
	s_waitcnt lgkmcnt(1)
	v_mfma_f32_32x32x16_bf16 v[20:35], v[88:91], v[84:87], v[20:35]
	s_waitcnt lgkmcnt(0)
	v_mfma_f32_32x32x16_bf16 v[36:51], v[92:95], v[80:83], v[36:51]
	v_mfma_f32_32x32x16_bf16 v[4:19], v[92:95], v[84:87], v[4:19]
	s_waitcnt vmcnt(1)
	s_barrier
; template <int NI, bool DEEP = true>
; DEV void gemm_tile(f32x16 (&acc)[2][NI], const bf16* __restrict__ A, int lda, const bf16* __restrict__ Bt, int ldb,
;                    int K, bf16* sA, bf16* sB) {
;     ...
;   G_LOAD(ra0, rb0, 0)
;   if (DEEP) {
;     if (64 < K) G_LOAD(ra1, rb1, 64)
;     for (int k0 = 0; k0 < K; k0 += 128) {
;       G_STEP(ra0, rb0, k0 + 128)
;       if (k0 + 64 < K) G_STEP(ra1, rb1, k0 + 192)
;     }
	ds_read_b128 v[88:91], v74 offset:38976
	ds_read_b128 v[80:83], v70 offset:32768
	ds_read_b128 v[84:87], v70 offset:36864
	ds_read_b128 v[92:95], v74 offset:43072
	s_waitcnt lgkmcnt(2)
	v_mfma_f32_32x32x16_bf16 v[52:67], v[88:91], v[80:83], v[52:67]
	s_add_u32 m0, s16, 0x0
	s_nop 0
	global_load_lds_dwordx4 v68, s[98:99]
	s_add_u32 m0, s16, 0x400
	s_add_u32 s14, s98, 0x4000
	s_addc_u32 s15, s99, 0
	global_load_lds_dwordx4 v69, s[14:15]
	ds_read_b128 v[104:107], v75 offset:38976
	ds_read_b128 v[96:99], v71 offset:32768
	s_waitcnt lgkmcnt(3)
	v_mfma_f32_32x32x16_bf16 v[20:35], v[88:91], v[84:87], v[20:35]
	s_add_u32 m0, s16, 0x800
	s_add_u32 s14, s98, 0x8000
	s_addc_u32 s15, s99, 0
	global_load_lds_dwordx4 v68, s[14:15]
	s_add_u32 m0, s16, 0xc00
	s_add_u32 s14, s98, 0xc000
	s_addc_u32 s15, s99, 0
	global_load_lds_dwordx4 v69, s[14:15]
	ds_read_b128 v[100:103], v71 offset:36864
	s_waitcnt lgkmcnt(3)
	v_mfma_f32_32x32x16_bf16 v[36:51], v[92:95], v[80:83], v[36:51]
	s_add_u32 m0, s16, 0x4000
	s_nop 0
	global_load_lds_dwordx4 v68, s[100:101]
	s_add_u32 m0, s16, 0x4400
	s_add_u32 s14, s100, 0x4000
	s_addc_u32 s15, s101, 0
	global_load_lds_dwordx4 v69, s[14:15]
	ds_read_b128 v[108:111], v75 offset:43072
	v_mfma_f32_32x32x16_bf16 v[4:19], v[92:95], v[84:87], v[4:19]
	s_add_u32 m0, s16, 0x4800
	s_add_u32 s14, s100, 0x8000
	s_addc_u32 s15, s101, 0
	global_load_lds_dwordx4 v68, s[14:15]
	s_add_u32 m0, s16, 0x4c00
	s_add_u32 s14, s100, 0xc000
	s_addc_u32 s15, s101, 0
	global_load_lds_dwordx4 v69, s[14:15]
	s_waitcnt lgkmcnt(2)
	v_mfma_f32_32x32x16_bf16 v[52:67], v[104:107], v[96:99], v[52:67]
	s_add_u32 s98, s98, 0x80
	s_addc_u32 s99, s99, 0
	s_add_u32 s100, s100, 0x80
	s_addc_u32 s101, s101, 0
	global_load_dwordx4 v[190:193], v242, s[30:31] offset:16
	s_add_u32 s30, s30, 0x10000
	s_addc_u32 s31, s31, 0
	ds_read_b128 v[120:123], v76 offset:38976
	ds_read_b128 v[112:115], v72 offset:32768
	s_waitcnt lgkmcnt(3)
	v_mfma_f32_32x32x16_bf16 v[20:35], v[104:107], v[100:103], v[20:35]
	ds_read_b128 v[116:119], v72 offset:36864
	s_waitcnt lgkmcnt(3)
	v_mfma_f32_32x32x16_bf16 v[36:51], v[108:111], v[96:99], v[36:51]
	ds_read_b128 v[124:127], v76 offset:43072
	v_mfma_f32_32x32x16_bf16 v[4:19], v[108:111], v[100:103], v[4:19]
	s_waitcnt lgkmcnt(2)
	v_mfma_f32_32x32x16_bf16 v[52:67], v[120:123], v[112:115], v[52:67]
	ds_read_b128 v[88:91], v77 offset:38976
	ds_read_b128 v[80:83], v73 offset:32768
	s_waitcnt lgkmcnt(3)
	v_mfma_f32_32x32x16_bf16 v[20:35], v[120:123], v[116:119], v[20:35]
	ds_read_b128 v[84:87], v73 offset:36864
	s_waitcnt lgkmcnt(3)
	v_mfma_f32_32x32x16_bf16 v[36:51], v[124:127], v[112:115], v[36:51]
	ds_read_b128 v[92:95], v77 offset:43072
	v_mfma_f32_32x32x16_bf16 v[4:19], v[124:127], v[116:119], v[4:19]
	s_waitcnt lgkmcnt(2)
	v_mfma_f32_32x32x16_bf16 v[52:67], v[88:91], v[80:83], v[52:67]
	s_waitcnt lgkmcnt(1)
	v_mfma_f32_32x32x16_bf16 v[20:35], v[88:91], v[84:87], v[20:35]
	s_waitcnt lgkmcnt(0)
	v_mfma_f32_32x32x16_bf16 v[36:51], v[92:95], v[80:83], v[36:51]
	v_mfma_f32_32x32x16_bf16 v[4:19], v[92:95], v[84:87], v[4:19]
	s_waitcnt vmcnt(1)
	s_barrier
	ds_read_b128 v[88:91], v74 offset:0
	ds_read_b128 v[80:83], v70 offset:0
	ds_read_b128 v[84:87], v70 offset:4096
	ds_read_b128 v[92:95], v74 offset:4096
	s_waitcnt lgkmcnt(2)
	v_mfma_f32_32x32x16_bf16 v[52:67], v[88:91], v[80:83], v[52:67]
	s_add_u32 m0, s16, 0x8000
	s_nop 0
	global_load_lds_dwordx4 v68, s[98:99]
	s_add_u32 m0, s16, 0x8400
	s_add_u32 s14, s98, 0x4000
	s_addc_u32 s15, s99, 0
	global_load_lds_dwordx4 v69, s[14:15]
	ds_read_b128 v[104:107], v75 offset:0
	ds_read_b128 v[96:99], v71 offset:0
	s_waitcnt lgkmcnt(3)
	v_mfma_f32_32x32x16_bf16 v[20:35], v[88:91], v[84:87], v[20:35]
	s_add_u32 m0, s16, 0x8800
	s_add_u32 s14, s98, 0x8000
	s_addc_u32 s15, s99, 0
	global_load_lds_dwordx4 v68, s[14:15]
	s_add_u32 m0, s16, 0x8c00
	s_add_u32 s14, s98, 0xc000
	s_addc_u32 s15, s99, 0
	global_load_lds_dwordx4 v69, s[14:15]
	ds_read_b128 v[100:103], v71 offset:4096
	s_waitcnt lgkmcnt(3)
	v_mfma_f32_32x32x16_bf16 v[36:51], v[92:95], v[80:83], v[36:51]
	s_add_u32 m0, s16, 0xd840
	s_nop 0
	global_load_lds_dwordx4 v68, s[100:101]
	s_add_u32 m0, s16, 0xdc40
	s_add_u32 s14, s100, 0x4000
	s_addc_u32 s15, s101, 0
	global_load_lds_dwordx4 v69, s[14:15]
	ds_read_b128 v[108:111], v75 offset:4096
	v_mfma_f32_32x32x16_bf16 v[4:19], v[92:95], v[84:87], v[4:19]
	s_add_u32 m0, s16, 0xe040
	s_add_u32 s14, s100, 0x8000
	s_addc_u32 s15, s101, 0
	global_load_lds_dwordx4 v68, s[14:15]
	s_add_u32 m0, s16, 0xe440
	s_add_u32 s14, s100, 0xc000
	s_addc_u32 s15, s101, 0
	global_load_lds_dwordx4 v69, s[14:15]
	s_waitcnt lgkmcnt(2)
	v_mfma_f32_32x32x16_bf16 v[52:67], v[104:107], v[96:99], v[52:67]
	s_add_u32 s98, s98, 0x80
	s_addc_u32 s99, s99, 0
	s_add_u32 s100, s100, 0x80
	s_addc_u32 s101, s101, 0
	global_load_dwordx4 v[210:213], v242, s[30:31]
	ds_read_b128 v[120:123], v76 offset:0
	ds_read_b128 v[112:115], v72 offset:0
	s_waitcnt lgkmcnt(3)
	v_mfma_f32_32x32x16_bf16 v[20:35], v[104:107], v[100:103], v[20:35]
	ds_read_b128 v[116:119], v72 offset:4096
	s_waitcnt lgkmcnt(3)
	v_mfma_f32_32x32x16_bf16 v[36:51], v[108:111], v[96:99], v[36:51]
	ds_read_b128 v[124:127], v76 offset:4096
	v_mfma_f32_32x32x16_bf16 v[4:19], v[108:111], v[100:103], v[4:19]
	s_waitcnt lgkmcnt(2)
	v_mfma_f32_32x32x16_bf16 v[52:67], v[120:123], v[112:115], v[52:67]
	ds_read_b128 v[88:91], v77 offset:0
	ds_read_b128 v[80:83], v73 offset:0
	s_waitcnt lgkmcnt(3)
	v_mfma_f32_32x32x16_bf16 v[20:35], v[120:123], v[116:119], v[20:35]
	ds_read_b128 v[84:87], v73 offset:4096
	s_waitcnt lgkmcnt(3)
	v_mfma_f32_32x32x16_bf16 v[36:51], v[124:127], v[112:115], v[36:51]
	ds_read_b128 v[92:95], v77 offset:4096
	v_mfma_f32_32x32x16_bf16 v[4:19], v[124:127], v[116:119], v[4:19]
	s_waitcnt lgkmcnt(2)
	v_mfma_f32_32x32x16_bf16 v[52:67], v[88:91], v[80:83], v[52:67]
	s_waitcnt lgkmcnt(1)
	v_mfma_f32_32x32x16_bf16 v[20:35], v[88:91], v[84:87], v[20:35]
	s_waitcnt lgkmcnt(0)
	v_mfma_f32_32x32x16_bf16 v[36:51], v[92:95], v[80:83], v[36:51]
	v_mfma_f32_32x32x16_bf16 v[4:19], v[92:95], v[84:87], v[4:19]
	s_waitcnt vmcnt(1)
	s_barrier
; template <int NI, bool DEEP = true>
; DEV void gemm_tile(f32x16 (&acc)[2][NI], const bf16* __restrict__ A, int lda, const bf16* __restrict__ Bt, int ldb,
;                    int K, bf16* sA, bf16* sB) {
;     ...
;   G_LOAD(ra0, rb0, 0)
;   if (DEEP) {
;     if (64 < K) G_LOAD(ra1, rb1, 64)
;     for (int k0 = 0; k0 < K; k0 += 128) {
;       G_STEP(ra0, rb0, k0 + 128)
;       if (k0 + 64 < K) G_STEP(ra1, rb1, k0 + 192)
;     }
	ds_read_b128 v[88:91], v74 offset:38976
	ds_read_b128 v[80:83], v70 offset:32768
	ds_read_b128 v[84:87], v70 offset:36864
	ds_read_b128 v[92:95], v74 offset:43072
	s_waitcnt lgkmcnt(2)
	v_mfma_f32_32x32x16_bf16 v[52:67], v[88:91], v[80:83], v[52:67]
	s_add_u32 m0, s16, 0x0
	s_nop 0
	global_load_lds_dwordx4 v68, s[98:99]
	s_add_u32 m0, s16, 0x400
	s_add_u32 s14, s98, 0x4000
	s_addc_u32 s15, s99, 0
	global_load_lds_dwordx4 v69, s[14:15]
	ds_read_b128 v[104:107], v75 offset:38976
	ds_read_b128 v[96:99], v71 offset:32768
	s_waitcnt lgkmcnt(3)
	v_mfma_f32_32x32x16_bf16 v[20:35], v[88:91], v[84:87], v[20:35]
	s_add_u32 m0, s16, 0x800
	s_add_u32 s14, s98, 0x8000
	s_addc_u32 s15, s99, 0
	global_load_lds_dwordx4 v68, s[14:15]
	s_add_u32 m0, s16, 0xc00
	s_add_u32 s14, s98, 0xc000
	s_addc_u32 s15, s99, 0
	global_load_lds_dwordx4 v69, s[14:15]
	ds_read_b128 v[100:103], v71 offset:36864
	s_waitcnt lgkmcnt(3)
	v_mfma_f32_32x32x16_bf16 v[36:51], v[92:95], v[80:83], v[36:51]
	s_add_u32 m0, s16, 0x4000
	s_nop 0
	global_load_lds_dwordx4 v68, s[100:101]
	s_add_u32 m0, s16, 0x4400
	s_add_u32 s14, s100, 0x4000
	s_addc_u32 s15, s101, 0
	global_load_lds_dwordx4 v69, s[14:15]
	ds_read_b128 v[108:111], v75 offset:43072
	v_mfma_f32_32x32x16_bf16 v[4:19], v[92:95], v[84:87], v[4:19]
	s_add_u32 m0, s16, 0x4800
	s_add_u32 s14, s100, 0x8000
	s_addc_u32 s15, s101, 0
	global_load_lds_dwordx4 v68, s[14:15]
	s_add_u32 m0, s16, 0x4c00
	s_add_u32 s14, s100, 0xc000
	s_addc_u32 s15, s101, 0
	global_load_lds_dwordx4 v69, s[14:15]
	s_waitcnt lgkmcnt(2)
	v_mfma_f32_32x32x16_bf16 v[52:67], v[104:107], v[96:99], v[52:67]
	s_add_u32 s98, s98, 0x80
	s_addc_u32 s99, s99, 0
	s_add_u32 s100, s100, 0x80
	s_addc_u32 s101, s101, 0
	global_load_dwordx4 v[214:217], v242, s[30:31] offset:16
	s_add_u32 s30, s30, 0x10000
	s_addc_u32 s31, s31, 0
	ds_read_b128 v[120:123], v76 offset:38976
	ds_read_b128 v[112:115], v72 offset:32768
	s_waitcnt lgkmcnt(3)
	v_mfma_f32_32x32x16_bf16 v[20:35], v[104:107], v[100:103], v[20:35]
	ds_read_b128 v[116:119], v72 offset:36864
	s_waitcnt lgkmcnt(3)
	v_mfma_f32_32x32x16_bf16 v[36:51], v[108:111], v[96:99], v[36:51]
	ds_read_b128 v[124:127], v76 offset:43072
	v_mfma_f32_32x32x16_bf16 v[4:19], v[108:111], v[100:103], v[4:19]
	s_waitcnt lgkmcnt(2)
	v_mfma_f32_32x32x16_bf16 v[52:67], v[120:123], v[112:115], v[52:67]
	ds_read_b128 v[88:91], v77 offset:38976
	ds_read_b128 v[80:83], v73 offset:32768
	s_waitcnt lgkmcnt(3)
	v_mfma_f32_32x32x16_bf16 v[20:35], v[120:123], v[116:119], v[20:35]
	ds_read_b128 v[84:87], v73 offset:36864
	s_waitcnt lgkmcnt(3)
	v_mfma_f32_32x32x16_bf16 v[36:51], v[124:127], v[112:115], v[36:51]
	ds_read_b128 v[92:95], v77 offset:43072
	v_mfma_f32_32x32x16_bf16 v[4:19], v[124:127], v[116:119], v[4:19]
	s_waitcnt lgkmcnt(2)
	v_mfma_f32_32x32x16_bf16 v[52:67], v[88:91], v[80:83], v[52:67]
	s_waitcnt lgkmcnt(1)
	v_mfma_f32_32x32x16_bf16 v[20:35], v[88:91], v[84:87], v[20:35]
	s_waitcnt lgkmcnt(0)
	v_mfma_f32_32x32x16_bf16 v[36:51], v[92:95], v[80:83], v[36:51]
	v_mfma_f32_32x32x16_bf16 v[4:19], v[92:95], v[84:87], v[4:19]
	s_waitcnt vmcnt(1)
	s_barrier
	ds_read_b128 v[88:91], v74 offset:0
	ds_read_b128 v[80:83], v70 offset:0
	ds_read_b128 v[84:87], v70 offset:4096
	ds_read_b128 v[92:95], v74 offset:4096
	s_waitcnt lgkmcnt(2)
	v_mfma_f32_32x32x16_bf16 v[52:67], v[88:91], v[80:83], v[52:67]
	s_add_u32 m0, s16, 0x8000
	s_nop 0
	global_load_lds_dwordx4 v68, s[98:99]
	s_add_u32 m0, s16, 0x8400
	s_add_u32 s14, s98, 0x4000
	s_addc_u32 s15, s99, 0
	global_load_lds_dwordx4 v69, s[14:15]
	ds_read_b128 v[104:107], v75 offset:0
	ds_read_b128 v[96:99], v71 offset:0
	s_waitcnt lgkmcnt(3)
	v_mfma_f32_32x32x16_bf16 v[20:35], v[88:91], v[84:87], v[20:35]
	s_add_u32 m0, s16, 0x8800
	s_add_u32 s14, s98, 0x8000
	s_addc_u32 s15, s99, 0
	global_load_lds_dwordx4 v68, s[14:15]
	s_add_u32 m0, s16, 0x8c00
	s_add_u32 s14, s98, 0xc000
	s_addc_u32 s15, s99, 0
	global_load_lds_dwordx4 v69, s[14:15]
	ds_read_b128 v[100:103], v71 offset:4096
	s_waitcnt lgkmcnt(3)
	v_mfma_f32_32x32x16_bf16 v[36:51], v[92:95], v[80:83], v[36:51]
	s_add_u32 m0, s16, 0xd840
	s_nop 0
	global_load_lds_dwordx4 v68, s[100:101]
	s_add_u32 m0, s16, 0xdc40
	s_add_u32 s14, s100, 0x4000
	s_addc_u32 s15, s101, 0
	global_load_lds_dwordx4 v69, s[14:15]
	ds_read_b128 v[108:111], v75 offset:4096
	v_mfma_f32_32x32x16_bf16 v[4:19], v[92:95], v[84:87], v[4:19]
	s_add_u32 m0, s16, 0xe040
	s_add_u32 s14, s100, 0x8000
	s_addc_u32 s15, s101, 0
	global_load_lds_dwordx4 v68, s[14:15]
	s_add_u32 m0, s16, 0xe440
	s_add_u32 s14, s100, 0xc000
	s_addc_u32 s15, s101, 0
	global_load_lds_dwordx4 v69, s[14:15]
	s_waitcnt lgkmcnt(2)
	v_mfma_f32_32x32x16_bf16 v[52:67], v[104:107], v[96:99], v[52:67]
	s_add_u32 s98, s98, 0x80
	s_addc_u32 s99, s99, 0
	s_add_u32 s100, s100, 0x80
	s_addc_u32 s101, s101, 0
	global_load_dwordx4 v[218:221], v242, s[30:31]
	ds_read_b128 v[120:123], v76 offset:0
	ds_read_b128 v[112:115], v72 offset:0
	s_waitcnt lgkmcnt(3)
	v_mfma_f32_32x32x16_bf16 v[20:35], v[104:107], v[100:103], v[20:35]
	ds_read_b128 v[116:119], v72 offset:4096
	s_waitcnt lgkmcnt(3)
	v_mfma_f32_32x32x16_bf16 v[36:51], v[108:111], v[96:99], v[36:51]
	ds_read_b128 v[124:127], v76 offset:4096
	v_mfma_f32_32x32x16_bf16 v[4:19], v[108:111], v[100:103], v[4:19]
	s_waitcnt lgkmcnt(2)
	v_mfma_f32_32x32x16_bf16 v[52:67], v[120:123], v[112:115], v[52:67]
	ds_read_b128 v[88:91], v77 offset:0
	ds_read_b128 v[80:83], v73 offset:0
	s_waitcnt lgkmcnt(3)
	v_mfma_f32_32x32x16_bf16 v[20:35], v[120:123], v[116:119], v[20:35]
	ds_read_b128 v[84:87], v73 offset:4096
	s_waitcnt lgkmcnt(3)
	v_mfma_f32_32x32x16_bf16 v[36:51], v[124:127], v[112:115], v[36:51]
	ds_read_b128 v[92:95], v77 offset:4096
	v_mfma_f32_32x32x16_bf16 v[4:19], v[124:127], v[116:119], v[4:19]
	s_waitcnt lgkmcnt(2)
	v_mfma_f32_32x32x16_bf16 v[52:67], v[88:91], v[80:83], v[52:67]
	s_waitcnt lgkmcnt(1)
	v_mfma_f32_32x32x16_bf16 v[20:35], v[88:91], v[84:87], v[20:35]
	s_waitcnt lgkmcnt(0)
	v_mfma_f32_32x32x16_bf16 v[36:51], v[92:95], v[80:83], v[36:51]
	v_mfma_f32_32x32x16_bf16 v[4:19], v[92:95], v[84:87], v[4:19]
	s_waitcnt vmcnt(1)
	s_barrier
; template <int NI, bool DEEP = true>
; DEV void gemm_tile(f32x16 (&acc)[2][NI], const bf16* __restrict__ A, int lda, const bf16* __restrict__ Bt, int ldb,
;                    int K, bf16* sA, bf16* sB) {
;     ...
;   G_LOAD(ra0, rb0, 0)
;   if (DEEP) {
;     if (64 < K) G_LOAD(ra1, rb1, 64)
;     for (int k0 = 0; k0 < K; k0 += 128) {
;       G_STEP(ra0, rb0, k0 + 128)
;       if (k0 + 64 < K) G_STEP(ra1, rb1, k0 + 192)
;     }
	ds_read_b128 v[88:91], v74 offset:38976
	ds_read_b128 v[80:83], v70 offset:32768
	ds_read_b128 v[84:87], v70 offset:36864
	ds_read_b128 v[92:95], v74 offset:43072
	s_waitcnt lgkmcnt(2)
	v_mfma_f32_32x32x16_bf16 v[52:67], v[88:91], v[80:83], v[52:67]
	s_add_u32 m0, s16, 0x0
	s_nop 0
	global_load_lds_dwordx4 v68, s[98:99]
	s_add_u32 m0, s16, 0x400
	s_add_u32 s14, s98, 0x4000
	s_addc_u32 s15, s99, 0
	global_load_lds_dwordx4 v69, s[14:15]
	ds_read_b128 v[104:107], v75 offset:38976
	ds_read_b128 v[96:99], v71 offset:32768
	s_waitcnt lgkmcnt(3)
	v_mfma_f32_32x32x16_bf16 v[20:35], v[88:91], v[84:87], v[20:35]
	s_add_u32 m0, s16, 0x800
	s_add_u32 s14, s98, 0x8000
	s_addc_u32 s15, s99, 0
	global_load_lds_dwordx4 v68, s[14:15]
	s_add_u32 m0, s16, 0xc00
	s_add_u32 s14, s98, 0xc000
	s_addc_u32 s15, s99, 0
	global_load_lds_dwordx4 v69, s[14:15]
	ds_read_b128 v[100:103], v71 offset:36864
	s_waitcnt lgkmcnt(3)
	v_mfma_f32_32x32x16_bf16 v[36:51], v[92:95], v[80:83], v[36:51]
	s_add_u32 m0, s16, 0x4000
	s_nop 0
	global_load_lds_dwordx4 v68, s[100:101]
	s_add_u32 m0, s16, 0x4400
	s_add_u32 s14, s100, 0x4000
	s_addc_u32 s15, s101, 0
	global_load_lds_dwordx4 v69, s[14:15]
	ds_read_b128 v[108:111], v75 offset:43072
	v_mfma_f32_32x32x16_bf16 v[4:19], v[92:95], v[84:87], v[4:19]
	s_add_u32 m0, s16, 0x4800
	s_add_u32 s14, s100, 0x8000
	s_addc_u32 s15, s101, 0
	global_load_lds_dwordx4 v68, s[14:15]
	s_add_u32 m0, s16, 0x4c00
	s_add_u32 s14, s100, 0xc000
	s_addc_u32 s15, s101, 0
	global_load_lds_dwordx4 v69, s[14:15]
	s_waitcnt lgkmcnt(2)
	v_mfma_f32_32x32x16_bf16 v[52:67], v[104:107], v[96:99], v[52:67]
	s_add_u32 s98, s98, 0x80
	s_addc_u32 s99, s99, 0
	s_add_u32 s100, s100, 0x80
	s_addc_u32 s101, s101, 0
	global_load_dwordx4 v[222:225], v242, s[30:31] offset:16
	s_add_u32 s30, s30, 0x10000
	s_addc_u32 s31, s31, 0
	ds_read_b128 v[120:123], v76 offset:38976
	ds_read_b128 v[112:115], v72 offset:32768
	s_waitcnt lgkmcnt(3)
	v_mfma_f32_32x32x16_bf16 v[20:35], v[104:107], v[100:103], v[20:35]
	ds_read_b128 v[116:119], v72 offset:36864
	s_waitcnt lgkmcnt(3)
	v_mfma_f32_32x32x16_bf16 v[36:51], v[108:111], v[96:99], v[36:51]
	ds_read_b128 v[124:127], v76 offset:43072
	v_mfma_f32_32x32x16_bf16 v[4:19], v[108:111], v[100:103], v[4:19]
	s_waitcnt lgkmcnt(2)
	v_mfma_f32_32x32x16_bf16 v[52:67], v[120:123], v[112:115], v[52:67]
	ds_read_b128 v[88:91], v77 offset:38976
	ds_read_b128 v[80:83], v73 offset:32768
	s_waitcnt lgkmcnt(3)
	v_mfma_f32_32x32x16_bf16 v[20:35], v[120:123], v[116:119], v[20:35]
	ds_read_b128 v[84:87], v73 offset:36864
	s_waitcnt lgkmcnt(3)
	v_mfma_f32_32x32x16_bf16 v[36:51], v[124:127], v[112:115], v[36:51]
	ds_read_b128 v[92:95], v77 offset:43072
	v_mfma_f32_32x32x16_bf16 v[4:19], v[124:127], v[116:119], v[4:19]
	s_waitcnt lgkmcnt(2)
	v_mfma_f32_32x32x16_bf16 v[52:67], v[88:91], v[80:83], v[52:67]
	s_waitcnt lgkmcnt(1)
	v_mfma_f32_32x32x16_bf16 v[20:35], v[88:91], v[84:87], v[20:35]
	s_waitcnt lgkmcnt(0)
	v_mfma_f32_32x32x16_bf16 v[36:51], v[92:95], v[80:83], v[36:51]
	v_mfma_f32_32x32x16_bf16 v[4:19], v[92:95], v[84:87], v[4:19]
	s_waitcnt vmcnt(1)
	s_barrier
	ds_read_b128 v[88:91], v74 offset:0
	ds_read_b128 v[80:83], v70 offset:0
	ds_read_b128 v[84:87], v70 offset:4096
	ds_read_b128 v[92:95], v74 offset:4096
	s_waitcnt lgkmcnt(2)
	v_mfma_f32_32x32x16_bf16 v[52:67], v[88:91], v[80:83], v[52:67]
	s_add_u32 m0, s16, 0x8000
	s_nop 0
	global_load_lds_dwordx4 v68, s[98:99]
	s_add_u32 m0, s16, 0x8400
	s_add_u32 s14, s98, 0x4000
	s_addc_u32 s15, s99, 0
	global_load_lds_dwordx4 v69, s[14:15]
	ds_read_b128 v[104:107], v75 offset:0
	ds_read_b128 v[96:99], v71 offset:0
	s_waitcnt lgkmcnt(3)
	v_mfma_f32_32x32x16_bf16 v[20:35], v[88:91], v[84:87], v[20:35]
	s_add_u32 m0, s16, 0x8800
	s_add_u32 s14, s98, 0x8000
	s_addc_u32 s15, s99, 0
	global_load_lds_dwordx4 v68, s[14:15]
	s_add_u32 m0, s16, 0x8c00
	s_add_u32 s14, s98, 0xc000
	s_addc_u32 s15, s99, 0
	global_load_lds_dwordx4 v69, s[14:15]
	ds_read_b128 v[100:103], v71 offset:4096
	s_waitcnt lgkmcnt(3)
	v_mfma_f32_32x32x16_bf16 v[36:51], v[92:95], v[80:83], v[36:51]
	s_add_u32 m0, s16, 0xd840
	s_nop 0
	global_load_lds_dwordx4 v68, s[100:101]
	s_add_u32 m0, s16, 0xdc40
	s_add_u32 s14, s100, 0x4000
	s_addc_u32 s15, s101, 0
	global_load_lds_dwordx4 v69, s[14:15]
	ds_read_b128 v[108:111], v75 offset:4096
	v_mfma_f32_32x32x16_bf16 v[4:19], v[92:95], v[84:87], v[4:19]
	s_add_u32 m0, s16, 0xe040
	s_add_u32 s14, s100, 0x8000
	s_addc_u32 s15, s101, 0
	global_load_lds_dwordx4 v68, s[14:15]
	s_add_u32 m0, s16, 0xe440
	s_add_u32 s14, s100, 0xc000
	s_addc_u32 s15, s101, 0
	global_load_lds_dwordx4 v69, s[14:15]
	s_waitcnt lgkmcnt(2)
	v_mfma_f32_32x32x16_bf16 v[52:67], v[104:107], v[96:99], v[52:67]
	s_add_u32 s98, s98, 0x80
	s_addc_u32 s99, s99, 0
	s_add_u32 s100, s100, 0x80
	s_addc_u32 s101, s101, 0
	global_load_dwordx4 v[226:229], v242, s[30:31]
	ds_read_b128 v[120:123], v76 offset:0
	ds_read_b128 v[112:115], v72 offset:0
	s_waitcnt lgkmcnt(3)
	v_mfma_f32_32x32x16_bf16 v[20:35], v[104:107], v[100:103], v[20:35]
	ds_read_b128 v[116:119], v72 offset:4096
	s_waitcnt lgkmcnt(3)
	v_mfma_f32_32x32x16_bf16 v[36:51], v[108:111], v[96:99], v[36:51]
	ds_read_b128 v[124:127], v76 offset:4096
	v_mfma_f32_32x32x16_bf16 v[4:19], v[108:111], v[100:103], v[4:19]
	s_waitcnt lgkmcnt(2)
	v_mfma_f32_32x32x16_bf16 v[52:67], v[120:123], v[112:115], v[52:67]
	ds_read_b128 v[88:91], v77 offset:0
	ds_read_b128 v[80:83], v73 offset:0
	s_waitcnt lgkmcnt(3)
	v_mfma_f32_32x32x16_bf16 v[20:35], v[120:123], v[116:119], v[20:35]
	ds_read_b128 v[84:87], v73 offset:4096
	s_waitcnt lgkmcnt(3)
	v_mfma_f32_32x32x16_bf16 v[36:51], v[124:127], v[112:115], v[36:51]
	ds_read_b128 v[92:95], v77 offset:4096
	v_mfma_f32_32x32x16_bf16 v[4:19], v[124:127], v[116:119], v[4:19]
	s_waitcnt lgkmcnt(2)
	v_mfma_f32_32x32x16_bf16 v[52:67], v[88:91], v[80:83], v[52:67]
	s_waitcnt lgkmcnt(1)
	v_mfma_f32_32x32x16_bf16 v[20:35], v[88:91], v[84:87], v[20:35]
	s_waitcnt lgkmcnt(0)
	v_mfma_f32_32x32x16_bf16 v[36:51], v[92:95], v[80:83], v[36:51]
	v_mfma_f32_32x32x16_bf16 v[4:19], v[92:95], v[84:87], v[4:19]
	s_waitcnt vmcnt(1)
	s_barrier
; template <int NI, bool DEEP = true>
; DEV void gemm_tile(f32x16 (&acc)[2][NI], const bf16* __restrict__ A, int lda, const bf16* __restrict__ Bt, int ldb,
;                    int K, bf16* sA, bf16* sB) {
;     ...
;   G_LOAD(ra0, rb0, 0)
;   if (DEEP) {
;     if (64 < K) G_LOAD(ra1, rb1, 64)
;     for (int k0 = 0; k0 < K; k0 += 128) {
;       G_STEP(ra0, rb0, k0 + 128)
;       if (k0 + 64 < K) G_STEP(ra1, rb1, k0 + 192)
;     }
	ds_read_b128 v[88:91], v74 offset:38976
	ds_read_b128 v[80:83], v70 offset:32768
	ds_read_b128 v[84:87], v70 offset:36864
	ds_read_b128 v[92:95], v74 offset:43072
	s_waitcnt lgkmcnt(2)
	v_mfma_f32_32x32x16_bf16 v[52:67], v[88:91], v[80:83], v[52:67]
	s_add_u32 m0, s16, 0x0
	s_nop 0
	global_load_lds_dwordx4 v68, s[98:99]
	s_add_u32 m0, s16, 0x400
	s_add_u32 s14, s98, 0x4000
	s_addc_u32 s15, s99, 0
	global_load_lds_dwordx4 v69, s[14:15]
	ds_read_b128 v[104:107], v75 offset:38976
	ds_read_b128 v[96:99], v71 offset:32768
	s_waitcnt lgkmcnt(3)
	v_mfma_f32_32x32x16_bf16 v[20:35], v[88:91], v[84:87], v[20:35]
	s_add_u32 m0, s16, 0x800
	s_add_u32 s14, s98, 0x8000
	s_addc_u32 s15, s99, 0
	global_load_lds_dwordx4 v68, s[14:15]
	s_add_u32 m0, s16, 0xc00
	s_add_u32 s14, s98, 0xc000
	s_addc_u32 s15, s99, 0
	global_load_lds_dwordx4 v69, s[14:15]
	ds_read_b128 v[100:103], v71 offset:36864
	s_waitcnt lgkmcnt(3)
	v_mfma_f32_32x32x16_bf16 v[36:51], v[92:95], v[80:83], v[36:51]
	s_add_u32 m0, s16, 0x4000
	s_nop 0
	global_load_lds_dwordx4 v68, s[100:101]
	s_add_u32 m0, s16, 0x4400
	s_add_u32 s14, s100, 0x4000
	s_addc_u32 s15, s101, 0
	global_load_lds_dwordx4 v69, s[14:15]
	ds_read_b128 v[108:111], v75 offset:43072
	v_mfma_f32_32x32x16_bf16 v[4:19], v[92:95], v[84:87], v[4:19]
	s_add_u32 m0, s16, 0x4800
	s_add_u32 s14, s100, 0x8000
	s_addc_u32 s15, s101, 0
	global_load_lds_dwordx4 v68, s[14:15]
	s_add_u32 m0, s16, 0x4c00
	s_add_u32 s14, s100, 0xc000
	s_addc_u32 s15, s101, 0
	global_load_lds_dwordx4 v69, s[14:15]
	s_waitcnt lgkmcnt(2)
	v_mfma_f32_32x32x16_bf16 v[52:67], v[104:107], v[96:99], v[52:67]
	s_add_u32 s98, s98, 0x80
	s_addc_u32 s99, s99, 0
	s_add_u32 s100, s100, 0x80
	s_addc_u32 s101, s101, 0
	global_load_dwordx4 v[230:233], v242, s[30:31] offset:16
	s_add_u32 s30, s30, 0x10000
	s_addc_u32 s31, s31, 0
	ds_read_b128 v[120:123], v76 offset:38976
	ds_read_b128 v[112:115], v72 offset:32768
	s_waitcnt lgkmcnt(3)
	v_mfma_f32_32x32x16_bf16 v[20:35], v[104:107], v[100:103], v[20:35]
	ds_read_b128 v[116:119], v72 offset:36864
	s_waitcnt lgkmcnt(3)
	v_mfma_f32_32x32x16_bf16 v[36:51], v[108:111], v[96:99], v[36:51]
	ds_read_b128 v[124:127], v76 offset:43072
	v_mfma_f32_32x32x16_bf16 v[4:19], v[108:111], v[100:103], v[4:19]
	s_waitcnt lgkmcnt(2)
	v_mfma_f32_32x32x16_bf16 v[52:67], v[120:123], v[112:115], v[52:67]
	ds_read_b128 v[88:91], v77 offset:38976
	ds_read_b128 v[80:83], v73 offset:32768
	s_waitcnt lgkmcnt(3)
	v_mfma_f32_32x32x16_bf16 v[20:35], v[120:123], v[116:119], v[20:35]
	ds_read_b128 v[84:87], v73 offset:36864
	s_waitcnt lgkmcnt(3)
	v_mfma_f32_32x32x16_bf16 v[36:51], v[124:127], v[112:115], v[36:51]
	ds_read_b128 v[92:95], v77 offset:43072
	v_mfma_f32_32x32x16_bf16 v[4:19], v[124:127], v[116:119], v[4:19]
	s_waitcnt lgkmcnt(2)
	v_mfma_f32_32x32x16_bf16 v[52:67], v[88:91], v[80:83], v[52:67]
	s_waitcnt lgkmcnt(1)
	v_mfma_f32_32x32x16_bf16 v[20:35], v[88:91], v[84:87], v[20:35]
	s_waitcnt lgkmcnt(0)
	v_mfma_f32_32x32x16_bf16 v[36:51], v[92:95], v[80:83], v[36:51]
	v_mfma_f32_32x32x16_bf16 v[4:19], v[92:95], v[84:87], v[4:19]
	s_waitcnt vmcnt(1)
	s_barrier
; template <int NI, bool DEEP = true>
; DEV void gemm_tile(f32x16 (&acc)[2][NI], const bf16* __restrict__ A, int lda, const bf16* __restrict__ Bt, int ldb,
;                    int K, bf16* sA, bf16* sB) {
;     ...
;   G_LOAD(ra0, rb0, 0)
;   if (DEEP) {
;     if (64 < K) G_LOAD(ra1, rb1, 64)
;     for (int k0 = 0; k0 < K; k0 += 128) {
;       G_STEP(ra0, rb0, k0 + 128)
;       if (k0 + 64 < K) G_STEP(ra1, rb1, k0 + 192)
;     }
	ds_read_b128 v[88:91], v74 offset:0
	ds_read_b128 v[80:83], v70 offset:0
	ds_read_b128 v[84:87], v70 offset:4096
	ds_read_b128 v[92:95], v74 offset:4096
	s_waitcnt lgkmcnt(2)
	v_mfma_f32_32x32x16_bf16 v[52:67], v[88:91], v[80:83], v[52:67]
	s_add_u32 m0, s16, 0x8000
	s_nop 0
	global_load_lds_dwordx4 v68, s[98:99]
	s_add_u32 m0, s16, 0x8400
	s_add_u32 s14, s98, 0x4000
	s_addc_u32 s15, s99, 0
	global_load_lds_dwordx4 v69, s[14:15]
	ds_read_b128 v[104:107], v75 offset:0
	ds_read_b128 v[96:99], v71 offset:0
	s_waitcnt lgkmcnt(3)
	v_mfma_f32_32x32x16_bf16 v[20:35], v[88:91], v[84:87], v[20:35]
	s_add_u32 m0, s16, 0x8800
	s_add_u32 s14, s98, 0x8000
	s_addc_u32 s15, s99, 0
	global_load_lds_dwordx4 v68, s[14:15]
	s_add_u32 m0, s16, 0x8c00
	s_add_u32 s14, s98, 0xc000
	s_addc_u32 s15, s99, 0
	global_load_lds_dwordx4 v69, s[14:15]
	ds_read_b128 v[100:103], v71 offset:4096
	s_waitcnt lgkmcnt(3)
	v_mfma_f32_32x32x16_bf16 v[36:51], v[92:95], v[80:83], v[36:51]
	s_add_u32 m0, s16, 0xd840
	s_nop 0
	global_load_lds_dwordx4 v68, s[100:101]
	s_add_u32 m0, s16, 0xdc40
	s_add_u32 s14, s100, 0x4000
	s_addc_u32 s15, s101, 0
	global_load_lds_dwordx4 v69, s[14:15]
	ds_read_b128 v[108:111], v75 offset:4096
	v_mfma_f32_32x32x16_bf16 v[4:19], v[92:95], v[84:87], v[4:19]
	s_add_u32 m0, s16, 0xe040
	s_add_u32 s14, s100, 0x8000
	s_addc_u32 s15, s101, 0
	global_load_lds_dwordx4 v68, s[14:15]
	s_add_u32 m0, s16, 0xe440
	s_add_u32 s14, s100, 0xc000
	s_addc_u32 s15, s101, 0
	global_load_lds_dwordx4 v69, s[14:15]
	s_waitcnt lgkmcnt(2)
	v_mfma_f32_32x32x16_bf16 v[52:67], v[104:107], v[96:99], v[52:67]
	s_add_u32 s98, s98, 0x80
	s_addc_u32 s99, s99, 0
	s_add_u32 s100, s100, 0x80
	s_addc_u32 s101, s101, 0
	global_load_dwordx4 v[234:237], v242, s[30:31]
	ds_read_b128 v[120:123], v76 offset:0
	ds_read_b128 v[112:115], v72 offset:0
	s_waitcnt lgkmcnt(3)
	v_mfma_f32_32x32x16_bf16 v[20:35], v[104:107], v[100:103], v[20:35]
	ds_read_b128 v[116:119], v72 offset:4096
	s_waitcnt lgkmcnt(3)
	v_mfma_f32_32x32x16_bf16 v[36:51], v[108:111], v[96:99], v[36:51]
	ds_read_b128 v[124:127], v76 offset:4096
	v_mfma_f32_32x32x16_bf16 v[4:19], v[108:111], v[100:103], v[4:19]
	s_waitcnt lgkmcnt(2)
	v_mfma_f32_32x32x16_bf16 v[52:67], v[120:123], v[112:115], v[52:67]
	ds_read_b128 v[88:91], v77 offset:0
	ds_read_b128 v[80:83], v73 offset:0
	s_waitcnt lgkmcnt(3)
	v_mfma_f32_32x32x16_bf16 v[20:35], v[120:123], v[116:119], v[20:35]
	ds_read_b128 v[84:87], v73 offset:4096
	s_waitcnt lgkmcnt(3)
	v_mfma_f32_32x32x16_bf16 v[36:51], v[124:127], v[112:115], v[36:51]
	ds_read_b128 v[92:95], v77 offset:4096
	v_mfma_f32_32x32x16_bf16 v[4:19], v[124:127], v[116:119], v[4:19]
	s_waitcnt lgkmcnt(2)
	v_mfma_f32_32x32x16_bf16 v[52:67], v[88:91], v[80:83], v[52:67]
	s_waitcnt lgkmcnt(1)
	v_mfma_f32_32x32x16_bf16 v[20:35], v[88:91], v[84:87], v[20:35]
	s_waitcnt lgkmcnt(0)
	v_mfma_f32_32x32x16_bf16 v[36:51], v[92:95], v[80:83], v[36:51]
	v_mfma_f32_32x32x16_bf16 v[4:19], v[92:95], v[84:87], v[4:19]
	s_waitcnt vmcnt(1)
	s_barrier
	ds_read_b128 v[88:91], v74 offset:38976
	ds_read_b128 v[80:83], v70 offset:32768
	ds_read_b128 v[84:87], v70 offset:36864
	ds_read_b128 v[92:95], v74 offset:43072
	s_waitcnt lgkmcnt(2)
	v_mfma_f32_32x32x16_bf16 v[52:67], v[88:91], v[80:83], v[52:67]
	global_load_dwordx4 v[238:241], v242, s[30:31] offset:16
	ds_read_b128 v[104:107], v75 offset:38976
	ds_read_b128 v[96:99], v71 offset:32768
	s_waitcnt lgkmcnt(3)
	v_mfma_f32_32x32x16_bf16 v[20:35], v[88:91], v[84:87], v[20:35]
	ds_read_b128 v[100:103], v71 offset:36864
	s_waitcnt lgkmcnt(3)
	v_mfma_f32_32x32x16_bf16 v[36:51], v[92:95], v[80:83], v[36:51]
	ds_read_b128 v[108:111], v75 offset:43072
	v_mfma_f32_32x32x16_bf16 v[4:19], v[92:95], v[84:87], v[4:19]
	s_waitcnt lgkmcnt(2)
	v_mfma_f32_32x32x16_bf16 v[52:67], v[104:107], v[96:99], v[52:67]
	ds_read_b128 v[120:123], v76 offset:38976
	ds_read_b128 v[112:115], v72 offset:32768
	s_waitcnt lgkmcnt(3)
	v_mfma_f32_32x32x16_bf16 v[20:35], v[104:107], v[100:103], v[20:35]
	ds_read_b128 v[116:119], v72 offset:36864
	s_waitcnt lgkmcnt(3)
	v_mfma_f32_32x32x16_bf16 v[36:51], v[108:111], v[96:99], v[36:51]
	ds_read_b128 v[124:127], v76 offset:43072
	v_mfma_f32_32x32x16_bf16 v[4:19], v[108:111], v[100:103], v[4:19]
	s_waitcnt lgkmcnt(2)
	v_mfma_f32_32x32x16_bf16 v[52:67], v[120:123], v[112:115], v[52:67]
	ds_read_b128 v[88:91], v77 offset:38976
	ds_read_b128 v[80:83], v73 offset:32768
	s_waitcnt lgkmcnt(3)
	v_mfma_f32_32x32x16_bf16 v[20:35], v[120:123], v[116:119], v[20:35]
	ds_read_b128 v[84:87], v73 offset:36864
	s_waitcnt lgkmcnt(3)
	v_mfma_f32_32x32x16_bf16 v[36:51], v[124:127], v[112:115], v[36:51]
	ds_read_b128 v[92:95], v77 offset:43072
	v_mfma_f32_32x32x16_bf16 v[4:19], v[124:127], v[116:119], v[4:19]
	s_waitcnt lgkmcnt(2)
	v_mfma_f32_32x32x16_bf16 v[52:67], v[88:91], v[80:83], v[52:67]
	s_waitcnt lgkmcnt(1)
	v_mfma_f32_32x32x16_bf16 v[20:35], v[88:91], v[84:87], v[20:35]
	s_waitcnt lgkmcnt(0)
	v_mfma_f32_32x32x16_bf16 v[36:51], v[92:95], v[80:83], v[36:51]
	v_mfma_f32_32x32x16_bf16 v[4:19], v[92:95], v[84:87], v[4:19]
	s_nop 7
	s_nop 7
